# EpiPle (P11) epilogue hand-written: X/PROJ loads prefetched 8 sub-blocks ahead, packed f32 sigmoid; P4 last-segment epilogue packed
# speedup vs baseline: 1.0327x; 1.0003x over previous
; DEV float bflo(unsigned w) { return __uint_as_float(w << 16); }
; DEV float bfhi(unsigned w) { return __uint_as_float(w & 0xffff0000u); }
; DEV float sigmoidf_(float x) { return 1.0f / (1.0f + __expf(-x)); }
;   DEV void operator()(const f32x4 (&acc)[2][2][4][2], const Unit& u, int wr, int wc, int fr, int fq) const {
;     const int row0 = u.pm * BM + wr * 64 + fr, col0 = u.pn * BM + wc * 32 + 4 * fq;
; #pragma unroll
;     for (int ai = 0; ai < 2; ++ai)
; #pragma unroll
;       for (int mp = 0; mp < 2; ++mp) {
;         f32x4 xv[2][2][2]; u32x2 pw[2][2][2];
; #pragma unroll
;         for (int mm = 0; mm < 2; ++mm)
; #pragma unroll
;           for (int bj = 0; bj < 2; ++bj)
; #pragma unroll
;             for (int n = 0; n < 2; ++n) {
;               const size_t o = (size_t)(row0 + ai * HALF + (mp * 2 + mm) * 16) * D + col0 + bj * HALF + n * 16;
;               pw[mm][bj][n] = *(const u32x2*)(PROJ + o);
;               xv[mm][bj][n] = *(const f32x4*)(X + o);
;             }
; #pragma unroll
;         for (int mm = 0; mm < 2; ++mm)
; #pragma unroll
;           for (int bj = 0; bj < 2; ++bj)
; #pragma unroll
;             for (int n = 0; n < 2; ++n) {
;               const size_t o = (size_t)(row0 + ai * HALF + (mp * 2 + mm) * 16) * D + col0 + bj * HALF + n * 16;
;               const f32x4 v = acc[ai][bj][mp * 2 + mm][n];
;               f32x4 x = xv[mm][bj][n]; const u32x2 w = pw[mm][bj][n];
;               x[0] += sigmoidf_(v[0]) * bflo(w.x); x[1] += sigmoidf_(v[1]) * bfhi(w.x); x[2] += sigmoidf_(v[2]) * bflo(w.y); x[3] += sigmoidf_(v[3]) * bfhi(w.y);
;               *(f32x4*)(X + o) = x;
;             }
;         asm volatile("" ::: "memory");
;       }
;   }
.LBB0_133:
	v_lshl_add_u32 v166, s27, 8, v177
	v_lshl_or_b32 v167, s42, 8, v218
	s_mov_b64 s[56:57], s[22:23]
	s_mov_b64 s[58:59], s[40:41]
	s_mov_b64 s[68:69], s[22:23]
	s_mov_b32 s70, 0xbfb8aa3b
	s_mov_b32 s71, 0xbfb8aa3b
	v_lshlrev_b32_e32 v156, 11, v166
	v_lshl_add_u32 v167, v167, 1, v156
	v_lshlrev_b32_e32 v166, 1, v167
	global_load_dwordx2 v[232:233], v167, s[58:59]
	global_load_dwordx4 v[180:183], v166, s[56:57]
	global_load_dwordx2 v[234:235], v167, s[58:59] offset:32
	global_load_dwordx4 v[184:187], v166, s[56:57] offset:64
	global_load_dwordx2 v[236:237], v167, s[58:59] offset:256
	global_load_dwordx4 v[188:191], v166, s[56:57] offset:512
	global_load_dwordx2 v[238:239], v167, s[58:59] offset:288
	global_load_dwordx4 v[192:195], v166, s[56:57] offset:576
	s_add_u32 s56, s56, 0x10000
	s_addc_u32 s57, s57, 0
	s_add_u32 s58, s58, 0x8000
	s_addc_u32 s59, s59, 0
	global_load_dwordx2 v[148:149], v167, s[58:59]
	global_load_dwordx4 v[196:199], v166, s[56:57]
	global_load_dwordx2 v[150:151], v167, s[58:59] offset:32
	global_load_dwordx4 v[220:223], v166, s[56:57] offset:64
	global_load_dwordx2 v[152:153], v167, s[58:59] offset:256
	global_load_dwordx4 v[224:227], v166, s[56:57] offset:512
	global_load_dwordx2 v[154:155], v167, s[58:59] offset:288
	global_load_dwordx4 v[228:231], v166, s[56:57] offset:576
	s_add_u32 s56, s56, 0x10000
	s_addc_u32 s57, s57, 0
	s_add_u32 s58, s58, 0x8000
	s_addc_u32 s59, s59, 0
	s_waitcnt vmcnt(14)
	v_pk_mul_f32 v[128:129], v[144:145], s[70:71]
	v_pk_mul_f32 v[130:131], v[146:147], s[70:71]
	v_lshlrev_b32_e32 v140, 16, v232
	v_exp_f32_e32 v128, v128
	v_exp_f32_e32 v129, v129
	v_exp_f32_e32 v130, v130
	v_exp_f32_e32 v131, v131
	v_and_b32_e32 v141, 0xffff0000, v232
	v_pk_add_f32 v[128:129], v[128:129], 1.0 op_sel_hi:[1,0]
	v_pk_add_f32 v[130:131], v[130:131], 1.0 op_sel_hi:[1,0]
	v_rcp_f32_e32 v132, v128
	v_rcp_f32_e32 v133, v129
	v_rcp_f32_e32 v134, v130
	v_rcp_f32_e32 v135, v131
	v_lshlrev_b32_e32 v142, 16, v233
	v_and_b32_e32 v143, 0xffff0000, v233
	v_pk_fma_f32 v[128:129], v[128:129], v[132:133], 1.0 op_sel_hi:[1,1,0] neg_lo:[1,0,0] neg_hi:[1,0,0]
	v_pk_fma_f32 v[130:131], v[130:131], v[134:135], 1.0 op_sel_hi:[1,1,0] neg_lo:[1,0,0] neg_hi:[1,0,0]
	v_pk_fma_f32 v[132:133], v[128:129], v[132:133], v[132:133]
	v_pk_fma_f32 v[134:135], v[130:131], v[134:135], v[134:135]
	v_pk_fma_f32 v[180:181], v[132:133], v[140:141], v[180:181]
	v_pk_fma_f32 v[182:183], v[134:135], v[142:143], v[182:183]
	global_store_dwordx4 v166, v[180:183], s[68:69]
	global_load_dwordx2 v[232:233], v167, s[58:59]
	global_load_dwordx4 v[180:183], v166, s[56:57]
	s_waitcnt vmcnt(15)
	v_pk_mul_f32 v[128:129], v[136:137], s[70:71]
	v_pk_mul_f32 v[130:131], v[138:139], s[70:71]
	v_lshlrev_b32_e32 v140, 16, v234
	v_exp_f32_e32 v128, v128
	v_exp_f32_e32 v129, v129
	v_exp_f32_e32 v130, v130
	v_exp_f32_e32 v131, v131
	v_and_b32_e32 v141, 0xffff0000, v234
	v_pk_add_f32 v[128:129], v[128:129], 1.0 op_sel_hi:[1,0]
	v_pk_add_f32 v[130:131], v[130:131], 1.0 op_sel_hi:[1,0]
	v_rcp_f32_e32 v132, v128
	v_rcp_f32_e32 v133, v129
	v_rcp_f32_e32 v134, v130
	v_rcp_f32_e32 v135, v131
	v_lshlrev_b32_e32 v142, 16, v235
	v_and_b32_e32 v143, 0xffff0000, v235
	v_pk_fma_f32 v[128:129], v[128:129], v[132:133], 1.0 op_sel_hi:[1,1,0] neg_lo:[1,0,0] neg_hi:[1,0,0]
	v_pk_fma_f32 v[130:131], v[130:131], v[134:135], 1.0 op_sel_hi:[1,1,0] neg_lo:[1,0,0] neg_hi:[1,0,0]
	v_pk_fma_f32 v[132:133], v[128:129], v[132:133], v[132:133]
	v_pk_fma_f32 v[134:135], v[130:131], v[134:135], v[134:135]
	v_pk_fma_f32 v[184:185], v[132:133], v[140:141], v[184:185]
	v_pk_fma_f32 v[186:187], v[134:135], v[142:143], v[186:187]
	global_store_dwordx4 v166, v[184:187], s[68:69] offset:64
	global_load_dwordx2 v[234:235], v167, s[58:59] offset:32
	global_load_dwordx4 v[184:187], v166, s[56:57] offset:64
	s_waitcnt vmcnt(16)
	v_pk_mul_f32 v[128:129], v[124:125], s[70:71]
	v_pk_mul_f32 v[130:131], v[126:127], s[70:71]
	v_lshlrev_b32_e32 v140, 16, v236
	v_exp_f32_e32 v128, v128
	v_exp_f32_e32 v129, v129
	v_exp_f32_e32 v130, v130
	v_exp_f32_e32 v131, v131
	v_and_b32_e32 v141, 0xffff0000, v236
	v_pk_add_f32 v[128:129], v[128:129], 1.0 op_sel_hi:[1,0]
	v_pk_add_f32 v[130:131], v[130:131], 1.0 op_sel_hi:[1,0]
	v_rcp_f32_e32 v132, v128
	v_rcp_f32_e32 v133, v129
	v_rcp_f32_e32 v134, v130
	v_rcp_f32_e32 v135, v131
	v_lshlrev_b32_e32 v142, 16, v237
	v_and_b32_e32 v143, 0xffff0000, v237
	v_pk_fma_f32 v[128:129], v[128:129], v[132:133], 1.0 op_sel_hi:[1,1,0] neg_lo:[1,0,0] neg_hi:[1,0,0]
	v_pk_fma_f32 v[130:131], v[130:131], v[134:135], 1.0 op_sel_hi:[1,1,0] neg_lo:[1,0,0] neg_hi:[1,0,0]
	v_pk_fma_f32 v[132:133], v[128:129], v[132:133], v[132:133]
	v_pk_fma_f32 v[134:135], v[130:131], v[134:135], v[134:135]
	v_pk_fma_f32 v[188:189], v[132:133], v[140:141], v[188:189]
	v_pk_fma_f32 v[190:191], v[134:135], v[142:143], v[190:191]
	global_store_dwordx4 v166, v[188:191], s[68:69] offset:512
	global_load_dwordx2 v[236:237], v167, s[58:59] offset:256
	global_load_dwordx4 v[188:191], v166, s[56:57] offset:512
	s_waitcnt vmcnt(17)
; DEV float bflo(unsigned w) { return __uint_as_float(w << 16); }
; DEV float bfhi(unsigned w) { return __uint_as_float(w & 0xffff0000u); }
; DEV float sigmoidf_(float x) { return 1.0f / (1.0f + __expf(-x)); }
;   DEV void operator()(const f32x4 (&acc)[2][2][4][2], const Unit& u, int wr, int wc, int fr, int fq) const {
;     const int row0 = u.pm * BM + wr * 64 + fr, col0 = u.pn * BM + wc * 32 + 4 * fq;
; #pragma unroll
;     for (int ai = 0; ai < 2; ++ai)
; #pragma unroll
;       for (int mp = 0; mp < 2; ++mp) {
;         f32x4 xv[2][2][2]; u32x2 pw[2][2][2];
; #pragma unroll
;         for (int mm = 0; mm < 2; ++mm)
; #pragma unroll
;           for (int bj = 0; bj < 2; ++bj)
; #pragma unroll
;             for (int n = 0; n < 2; ++n) {
;               const size_t o = (size_t)(row0 + ai * HALF + (mp * 2 + mm) * 16) * D + col0 + bj * HALF + n * 16;
;               pw[mm][bj][n] = *(const u32x2*)(PROJ + o);
;               xv[mm][bj][n] = *(const f32x4*)(X + o);
;             }
; #pragma unroll
;         for (int mm = 0; mm < 2; ++mm)
; #pragma unroll
;           for (int bj = 0; bj < 2; ++bj)
; #pragma unroll
;             for (int n = 0; n < 2; ++n) {
;               const size_t o = (size_t)(row0 + ai * HALF + (mp * 2 + mm) * 16) * D + col0 + bj * HALF + n * 16;
;               const f32x4 v = acc[ai][bj][mp * 2 + mm][n];
;               f32x4 x = xv[mm][bj][n]; const u32x2 w = pw[mm][bj][n];
;               x[0] += sigmoidf_(v[0]) * bflo(w.x); x[1] += sigmoidf_(v[1]) * bfhi(w.x); x[2] += sigmoidf_(v[2]) * bflo(w.y); x[3] += sigmoidf_(v[3]) * bfhi(w.y);
;               *(f32x4*)(X + o) = x;
;             }
;         asm volatile("" ::: "memory");
;       }
;   }
	v_pk_mul_f32 v[128:129], v[116:117], s[70:71]
	v_pk_mul_f32 v[130:131], v[118:119], s[70:71]
	v_lshlrev_b32_e32 v140, 16, v238
	v_exp_f32_e32 v128, v128
	v_exp_f32_e32 v129, v129
	v_exp_f32_e32 v130, v130
	v_exp_f32_e32 v131, v131
	v_and_b32_e32 v141, 0xffff0000, v238
	v_pk_add_f32 v[128:129], v[128:129], 1.0 op_sel_hi:[1,0]
	v_pk_add_f32 v[130:131], v[130:131], 1.0 op_sel_hi:[1,0]
	v_rcp_f32_e32 v132, v128
	v_rcp_f32_e32 v133, v129
	v_rcp_f32_e32 v134, v130
	v_rcp_f32_e32 v135, v131
	v_lshlrev_b32_e32 v142, 16, v239
	v_and_b32_e32 v143, 0xffff0000, v239
	v_pk_fma_f32 v[128:129], v[128:129], v[132:133], 1.0 op_sel_hi:[1,1,0] neg_lo:[1,0,0] neg_hi:[1,0,0]
	v_pk_fma_f32 v[130:131], v[130:131], v[134:135], 1.0 op_sel_hi:[1,1,0] neg_lo:[1,0,0] neg_hi:[1,0,0]
	v_pk_fma_f32 v[132:133], v[128:129], v[132:133], v[132:133]
	v_pk_fma_f32 v[134:135], v[130:131], v[134:135], v[134:135]
	v_pk_fma_f32 v[192:193], v[132:133], v[140:141], v[192:193]
	v_pk_fma_f32 v[194:195], v[134:135], v[142:143], v[194:195]
	global_store_dwordx4 v166, v[192:195], s[68:69] offset:576
	s_add_u32 s68, s68, 0x10000
	s_addc_u32 s69, s69, 0
	global_load_dwordx2 v[238:239], v167, s[58:59] offset:288
	global_load_dwordx4 v[192:195], v166, s[56:57] offset:576
	s_add_u32 s56, s56, 0x10000
	s_addc_u32 s57, s57, 0
	s_add_u32 s58, s58, 0x8000
	s_addc_u32 s59, s59, 0
	s_waitcnt vmcnt(18)
	v_pk_mul_f32 v[128:129], v[112:113], s[70:71]
	v_pk_mul_f32 v[130:131], v[114:115], s[70:71]
	v_lshlrev_b32_e32 v140, 16, v148
	v_exp_f32_e32 v128, v128
	v_exp_f32_e32 v129, v129
	v_exp_f32_e32 v130, v130
	v_exp_f32_e32 v131, v131
	v_and_b32_e32 v141, 0xffff0000, v148
	v_pk_add_f32 v[128:129], v[128:129], 1.0 op_sel_hi:[1,0]
	v_pk_add_f32 v[130:131], v[130:131], 1.0 op_sel_hi:[1,0]
	v_rcp_f32_e32 v132, v128
	v_rcp_f32_e32 v133, v129
	v_rcp_f32_e32 v134, v130
	v_rcp_f32_e32 v135, v131
	v_lshlrev_b32_e32 v142, 16, v149
	v_and_b32_e32 v143, 0xffff0000, v149
	v_pk_fma_f32 v[128:129], v[128:129], v[132:133], 1.0 op_sel_hi:[1,1,0] neg_lo:[1,0,0] neg_hi:[1,0,0]
	v_pk_fma_f32 v[130:131], v[130:131], v[134:135], 1.0 op_sel_hi:[1,1,0] neg_lo:[1,0,0] neg_hi:[1,0,0]
	v_pk_fma_f32 v[132:133], v[128:129], v[132:133], v[132:133]
	v_pk_fma_f32 v[134:135], v[130:131], v[134:135], v[134:135]
	v_pk_fma_f32 v[196:197], v[132:133], v[140:141], v[196:197]
	v_pk_fma_f32 v[198:199], v[134:135], v[142:143], v[198:199]
	global_store_dwordx4 v166, v[196:199], s[68:69]
	global_load_dwordx2 v[148:149], v167, s[58:59]
	global_load_dwordx4 v[196:199], v166, s[56:57]
	s_waitcnt vmcnt(19)
	v_pk_mul_f32 v[128:129], v[104:105], s[70:71]
	v_pk_mul_f32 v[130:131], v[106:107], s[70:71]
	v_lshlrev_b32_e32 v140, 16, v150
	v_exp_f32_e32 v128, v128
	v_exp_f32_e32 v129, v129
	v_exp_f32_e32 v130, v130
	v_exp_f32_e32 v131, v131
	v_and_b32_e32 v141, 0xffff0000, v150
	v_pk_add_f32 v[128:129], v[128:129], 1.0 op_sel_hi:[1,0]
	v_pk_add_f32 v[130:131], v[130:131], 1.0 op_sel_hi:[1,0]
	v_rcp_f32_e32 v132, v128
	v_rcp_f32_e32 v133, v129
	v_rcp_f32_e32 v134, v130
	v_rcp_f32_e32 v135, v131
	v_lshlrev_b32_e32 v142, 16, v151
	v_and_b32_e32 v143, 0xffff0000, v151
	v_pk_fma_f32 v[128:129], v[128:129], v[132:133], 1.0 op_sel_hi:[1,1,0] neg_lo:[1,0,0] neg_hi:[1,0,0]
	v_pk_fma_f32 v[130:131], v[130:131], v[134:135], 1.0 op_sel_hi:[1,1,0] neg_lo:[1,0,0] neg_hi:[1,0,0]
	v_pk_fma_f32 v[132:133], v[128:129], v[132:133], v[132:133]
	v_pk_fma_f32 v[134:135], v[130:131], v[134:135], v[134:135]
	v_pk_fma_f32 v[220:221], v[132:133], v[140:141], v[220:221]
	v_pk_fma_f32 v[222:223], v[134:135], v[142:143], v[222:223]
	global_store_dwordx4 v166, v[220:223], s[68:69] offset:64
	global_load_dwordx2 v[150:151], v167, s[58:59] offset:32
	global_load_dwordx4 v[220:223], v166, s[56:57] offset:64
	s_waitcnt vmcnt(20)
	v_pk_mul_f32 v[128:129], v[100:101], s[70:71]
	v_pk_mul_f32 v[130:131], v[102:103], s[70:71]
	v_lshlrev_b32_e32 v140, 16, v152
	v_exp_f32_e32 v128, v128
	v_exp_f32_e32 v129, v129
	v_exp_f32_e32 v130, v130
	v_exp_f32_e32 v131, v131
	v_and_b32_e32 v141, 0xffff0000, v152
	v_pk_add_f32 v[128:129], v[128:129], 1.0 op_sel_hi:[1,0]
	v_pk_add_f32 v[130:131], v[130:131], 1.0 op_sel_hi:[1,0]
	v_rcp_f32_e32 v132, v128
	v_rcp_f32_e32 v133, v129
	v_rcp_f32_e32 v134, v130
	v_rcp_f32_e32 v135, v131
	v_lshlrev_b32_e32 v142, 16, v153
	v_and_b32_e32 v143, 0xffff0000, v153
	v_pk_fma_f32 v[128:129], v[128:129], v[132:133], 1.0 op_sel_hi:[1,1,0] neg_lo:[1,0,0] neg_hi:[1,0,0]
	v_pk_fma_f32 v[130:131], v[130:131], v[134:135], 1.0 op_sel_hi:[1,1,0] neg_lo:[1,0,0] neg_hi:[1,0,0]
	v_pk_fma_f32 v[132:133], v[128:129], v[132:133], v[132:133]
	v_pk_fma_f32 v[134:135], v[130:131], v[134:135], v[134:135]
	v_pk_fma_f32 v[224:225], v[132:133], v[140:141], v[224:225]
	v_pk_fma_f32 v[226:227], v[134:135], v[142:143], v[226:227]
	global_store_dwordx4 v166, v[224:227], s[68:69] offset:512
	global_load_dwordx2 v[152:153], v167, s[58:59] offset:256
	global_load_dwordx4 v[224:227], v166, s[56:57] offset:512
	s_waitcnt vmcnt(21)
; DEV float bflo(unsigned w) { return __uint_as_float(w << 16); }
; DEV float bfhi(unsigned w) { return __uint_as_float(w & 0xffff0000u); }
; DEV float sigmoidf_(float x) { return 1.0f / (1.0f + __expf(-x)); }
;   DEV void operator()(const f32x4 (&acc)[2][2][4][2], const Unit& u, int wr, int wc, int fr, int fq) const {
;     const int row0 = u.pm * BM + wr * 64 + fr, col0 = u.pn * BM + wc * 32 + 4 * fq;
; #pragma unroll
;     for (int ai = 0; ai < 2; ++ai)
; #pragma unroll
;       for (int mp = 0; mp < 2; ++mp) {
;         f32x4 xv[2][2][2]; u32x2 pw[2][2][2];
; #pragma unroll
;         for (int mm = 0; mm < 2; ++mm)
; #pragma unroll
;           for (int bj = 0; bj < 2; ++bj)
; #pragma unroll
;             for (int n = 0; n < 2; ++n) {
;               const size_t o = (size_t)(row0 + ai * HALF + (mp * 2 + mm) * 16) * D + col0 + bj * HALF + n * 16;
;               pw[mm][bj][n] = *(const u32x2*)(PROJ + o);
;               xv[mm][bj][n] = *(const f32x4*)(X + o);
;             }
; #pragma unroll
;         for (int mm = 0; mm < 2; ++mm)
; #pragma unroll
;           for (int bj = 0; bj < 2; ++bj)
; #pragma unroll
;             for (int n = 0; n < 2; ++n) {
;               const size_t o = (size_t)(row0 + ai * HALF + (mp * 2 + mm) * 16) * D + col0 + bj * HALF + n * 16;
;               const f32x4 v = acc[ai][bj][mp * 2 + mm][n];
;               f32x4 x = xv[mm][bj][n]; const u32x2 w = pw[mm][bj][n];
;               x[0] += sigmoidf_(v[0]) * bflo(w.x); x[1] += sigmoidf_(v[1]) * bfhi(w.x); x[2] += sigmoidf_(v[2]) * bflo(w.y); x[3] += sigmoidf_(v[3]) * bfhi(w.y);
;               *(f32x4*)(X + o) = x;
;             }
;         asm volatile("" ::: "memory");
;       }
;   }
	v_pk_mul_f32 v[128:129], v[96:97], s[70:71]
	v_pk_mul_f32 v[130:131], v[98:99], s[70:71]
	v_lshlrev_b32_e32 v140, 16, v154
	v_exp_f32_e32 v128, v128
	v_exp_f32_e32 v129, v129
	v_exp_f32_e32 v130, v130
	v_exp_f32_e32 v131, v131
	v_and_b32_e32 v141, 0xffff0000, v154
	v_pk_add_f32 v[128:129], v[128:129], 1.0 op_sel_hi:[1,0]
	v_pk_add_f32 v[130:131], v[130:131], 1.0 op_sel_hi:[1,0]
	v_rcp_f32_e32 v132, v128
	v_rcp_f32_e32 v133, v129
	v_rcp_f32_e32 v134, v130
	v_rcp_f32_e32 v135, v131
	v_lshlrev_b32_e32 v142, 16, v155
	v_and_b32_e32 v143, 0xffff0000, v155
	v_pk_fma_f32 v[128:129], v[128:129], v[132:133], 1.0 op_sel_hi:[1,1,0] neg_lo:[1,0,0] neg_hi:[1,0,0]
	v_pk_fma_f32 v[130:131], v[130:131], v[134:135], 1.0 op_sel_hi:[1,1,0] neg_lo:[1,0,0] neg_hi:[1,0,0]
	v_pk_fma_f32 v[132:133], v[128:129], v[132:133], v[132:133]
	v_pk_fma_f32 v[134:135], v[130:131], v[134:135], v[134:135]
	v_pk_fma_f32 v[228:229], v[132:133], v[140:141], v[228:229]
	v_pk_fma_f32 v[230:231], v[134:135], v[142:143], v[230:231]
	global_store_dwordx4 v166, v[228:231], s[68:69] offset:576
	s_add_u32 s68, s68, 0x10000
	s_addc_u32 s69, s69, 0
	global_load_dwordx2 v[154:155], v167, s[58:59] offset:288
	global_load_dwordx4 v[228:231], v166, s[56:57] offset:576
	s_add_u32 s56, s56, 0x50000
	s_addc_u32 s57, s57, 0
	s_add_u32 s58, s58, 0x28000
	s_addc_u32 s59, s59, 0
	s_waitcnt vmcnt(21)
	v_pk_mul_f32 v[128:129], v[92:93], s[70:71]
	v_pk_mul_f32 v[130:131], v[94:95], s[70:71]
	v_lshlrev_b32_e32 v140, 16, v232
	v_exp_f32_e32 v128, v128
	v_exp_f32_e32 v129, v129
	v_exp_f32_e32 v130, v130
	v_exp_f32_e32 v131, v131
	v_and_b32_e32 v141, 0xffff0000, v232
	v_pk_add_f32 v[128:129], v[128:129], 1.0 op_sel_hi:[1,0]
	v_pk_add_f32 v[130:131], v[130:131], 1.0 op_sel_hi:[1,0]
	v_rcp_f32_e32 v132, v128
	v_rcp_f32_e32 v133, v129
	v_rcp_f32_e32 v134, v130
	v_rcp_f32_e32 v135, v131
	v_lshlrev_b32_e32 v142, 16, v233
	v_and_b32_e32 v143, 0xffff0000, v233
	v_pk_fma_f32 v[128:129], v[128:129], v[132:133], 1.0 op_sel_hi:[1,1,0] neg_lo:[1,0,0] neg_hi:[1,0,0]
	v_pk_fma_f32 v[130:131], v[130:131], v[134:135], 1.0 op_sel_hi:[1,1,0] neg_lo:[1,0,0] neg_hi:[1,0,0]
	v_pk_fma_f32 v[132:133], v[128:129], v[132:133], v[132:133]
	v_pk_fma_f32 v[134:135], v[130:131], v[134:135], v[134:135]
	v_pk_fma_f32 v[180:181], v[132:133], v[140:141], v[180:181]
	v_pk_fma_f32 v[182:183], v[134:135], v[142:143], v[182:183]
	global_store_dwordx4 v166, v[180:183], s[68:69]
	global_load_dwordx2 v[232:233], v167, s[58:59]
	global_load_dwordx4 v[180:183], v166, s[56:57]
	s_waitcnt vmcnt(21)
	v_pk_mul_f32 v[128:129], v[88:89], s[70:71]
	v_pk_mul_f32 v[130:131], v[90:91], s[70:71]
	v_lshlrev_b32_e32 v140, 16, v234
	v_exp_f32_e32 v128, v128
	v_exp_f32_e32 v129, v129
	v_exp_f32_e32 v130, v130
	v_exp_f32_e32 v131, v131
	v_and_b32_e32 v141, 0xffff0000, v234
	v_pk_add_f32 v[128:129], v[128:129], 1.0 op_sel_hi:[1,0]
	v_pk_add_f32 v[130:131], v[130:131], 1.0 op_sel_hi:[1,0]
	v_rcp_f32_e32 v132, v128
	v_rcp_f32_e32 v133, v129
	v_rcp_f32_e32 v134, v130
	v_rcp_f32_e32 v135, v131
	v_lshlrev_b32_e32 v142, 16, v235
	v_and_b32_e32 v143, 0xffff0000, v235
	v_pk_fma_f32 v[128:129], v[128:129], v[132:133], 1.0 op_sel_hi:[1,1,0] neg_lo:[1,0,0] neg_hi:[1,0,0]
	v_pk_fma_f32 v[130:131], v[130:131], v[134:135], 1.0 op_sel_hi:[1,1,0] neg_lo:[1,0,0] neg_hi:[1,0,0]
	v_pk_fma_f32 v[132:133], v[128:129], v[132:133], v[132:133]
	v_pk_fma_f32 v[134:135], v[130:131], v[134:135], v[134:135]
	v_pk_fma_f32 v[184:185], v[132:133], v[140:141], v[184:185]
	v_pk_fma_f32 v[186:187], v[134:135], v[142:143], v[186:187]
	global_store_dwordx4 v166, v[184:187], s[68:69] offset:64
	global_load_dwordx2 v[234:235], v167, s[58:59] offset:32
	global_load_dwordx4 v[184:187], v166, s[56:57] offset:64
	s_waitcnt vmcnt(21)
	v_pk_mul_f32 v[128:129], v[84:85], s[70:71]
	v_pk_mul_f32 v[130:131], v[86:87], s[70:71]
	v_lshlrev_b32_e32 v140, 16, v236
	v_exp_f32_e32 v128, v128
	v_exp_f32_e32 v129, v129
	v_exp_f32_e32 v130, v130
	v_exp_f32_e32 v131, v131
	v_and_b32_e32 v141, 0xffff0000, v236
	v_pk_add_f32 v[128:129], v[128:129], 1.0 op_sel_hi:[1,0]
	v_pk_add_f32 v[130:131], v[130:131], 1.0 op_sel_hi:[1,0]
	v_rcp_f32_e32 v132, v128
	v_rcp_f32_e32 v133, v129
	v_rcp_f32_e32 v134, v130
	v_rcp_f32_e32 v135, v131
	v_lshlrev_b32_e32 v142, 16, v237
	v_and_b32_e32 v143, 0xffff0000, v237
	v_pk_fma_f32 v[128:129], v[128:129], v[132:133], 1.0 op_sel_hi:[1,1,0] neg_lo:[1,0,0] neg_hi:[1,0,0]
	v_pk_fma_f32 v[130:131], v[130:131], v[134:135], 1.0 op_sel_hi:[1,1,0] neg_lo:[1,0,0] neg_hi:[1,0,0]
	v_pk_fma_f32 v[132:133], v[128:129], v[132:133], v[132:133]
	v_pk_fma_f32 v[134:135], v[130:131], v[134:135], v[134:135]
	v_pk_fma_f32 v[188:189], v[132:133], v[140:141], v[188:189]
	v_pk_fma_f32 v[190:191], v[134:135], v[142:143], v[190:191]
	global_store_dwordx4 v166, v[188:191], s[68:69] offset:512
	global_load_dwordx2 v[236:237], v167, s[58:59] offset:256
	global_load_dwordx4 v[188:191], v166, s[56:57] offset:512
	s_waitcnt vmcnt(21)
	v_pk_mul_f32 v[128:129], v[80:81], s[70:71]
	v_pk_mul_f32 v[130:131], v[82:83], s[70:71]
	v_lshlrev_b32_e32 v140, 16, v238
	v_exp_f32_e32 v128, v128
	v_exp_f32_e32 v129, v129
	v_exp_f32_e32 v130, v130
	v_exp_f32_e32 v131, v131
	v_and_b32_e32 v141, 0xffff0000, v238
	v_pk_add_f32 v[128:129], v[128:129], 1.0 op_sel_hi:[1,0]
	v_pk_add_f32 v[130:131], v[130:131], 1.0 op_sel_hi:[1,0]
	v_rcp_f32_e32 v132, v128
	v_rcp_f32_e32 v133, v129
	v_rcp_f32_e32 v134, v130
	v_rcp_f32_e32 v135, v131
	v_lshlrev_b32_e32 v142, 16, v239
	v_and_b32_e32 v143, 0xffff0000, v239
	v_pk_fma_f32 v[128:129], v[128:129], v[132:133], 1.0 op_sel_hi:[1,1,0] neg_lo:[1,0,0] neg_hi:[1,0,0]
	v_pk_fma_f32 v[130:131], v[130:131], v[134:135], 1.0 op_sel_hi:[1,1,0] neg_lo:[1,0,0] neg_hi:[1,0,0]
	v_pk_fma_f32 v[132:133], v[128:129], v[132:133], v[132:133]
	v_pk_fma_f32 v[134:135], v[130:131], v[134:135], v[134:135]
	v_pk_fma_f32 v[192:193], v[132:133], v[140:141], v[192:193]
	v_pk_fma_f32 v[194:195], v[134:135], v[142:143], v[194:195]
	global_store_dwordx4 v166, v[192:195], s[68:69] offset:576
	s_add_u32 s68, s68, 0x10000
	s_addc_u32 s69, s69, 0
	global_load_dwordx2 v[238:239], v167, s[58:59] offset:288
	global_load_dwordx4 v[192:195], v166, s[56:57] offset:576
	s_add_u32 s56, s56, 0x10000
	s_addc_u32 s57, s57, 0
	s_add_u32 s58, s58, 0x8000
	s_addc_u32 s59, s59, 0
	s_waitcnt vmcnt(21)
; DEV float bflo(unsigned w) { return __uint_as_float(w << 16); }
; DEV float bfhi(unsigned w) { return __uint_as_float(w & 0xffff0000u); }
; DEV float sigmoidf_(float x) { return 1.0f / (1.0f + __expf(-x)); }
;   DEV void operator()(const f32x4 (&acc)[2][2][4][2], const Unit& u, int wr, int wc, int fr, int fq) const {
;     const int row0 = u.pm * BM + wr * 64 + fr, col0 = u.pn * BM + wc * 32 + 4 * fq;
; #pragma unroll
;     for (int ai = 0; ai < 2; ++ai)
; #pragma unroll
;       for (int mp = 0; mp < 2; ++mp) {
;         f32x4 xv[2][2][2]; u32x2 pw[2][2][2];
; #pragma unroll
;         for (int mm = 0; mm < 2; ++mm)
; #pragma unroll
;           for (int bj = 0; bj < 2; ++bj)
; #pragma unroll
;             for (int n = 0; n < 2; ++n) {
;               const size_t o = (size_t)(row0 + ai * HALF + (mp * 2 + mm) * 16) * D + col0 + bj * HALF + n * 16;
;               pw[mm][bj][n] = *(const u32x2*)(PROJ + o);
;               xv[mm][bj][n] = *(const f32x4*)(X + o);
;             }
; #pragma unroll
;         for (int mm = 0; mm < 2; ++mm)
; #pragma unroll
;           for (int bj = 0; bj < 2; ++bj)
; #pragma unroll
;             for (int n = 0; n < 2; ++n) {
;               const size_t o = (size_t)(row0 + ai * HALF + (mp * 2 + mm) * 16) * D + col0 + bj * HALF + n * 16;
;               const f32x4 v = acc[ai][bj][mp * 2 + mm][n];
;               f32x4 x = xv[mm][bj][n]; const u32x2 w = pw[mm][bj][n];
;               x[0] += sigmoidf_(v[0]) * bflo(w.x); x[1] += sigmoidf_(v[1]) * bfhi(w.x); x[2] += sigmoidf_(v[2]) * bflo(w.y); x[3] += sigmoidf_(v[3]) * bfhi(w.y);
;               *(f32x4*)(X + o) = x;
;             }
;         asm volatile("" ::: "memory");
;       }
;   }
	v_pk_mul_f32 v[128:129], v[76:77], s[70:71]
	v_pk_mul_f32 v[130:131], v[78:79], s[70:71]
	v_lshlrev_b32_e32 v140, 16, v148
	v_exp_f32_e32 v128, v128
	v_exp_f32_e32 v129, v129
	v_exp_f32_e32 v130, v130
	v_exp_f32_e32 v131, v131
	v_and_b32_e32 v141, 0xffff0000, v148
	v_pk_add_f32 v[128:129], v[128:129], 1.0 op_sel_hi:[1,0]
	v_pk_add_f32 v[130:131], v[130:131], 1.0 op_sel_hi:[1,0]
	v_rcp_f32_e32 v132, v128
	v_rcp_f32_e32 v133, v129
	v_rcp_f32_e32 v134, v130
	v_rcp_f32_e32 v135, v131
	v_lshlrev_b32_e32 v142, 16, v149
	v_and_b32_e32 v143, 0xffff0000, v149
	v_pk_fma_f32 v[128:129], v[128:129], v[132:133], 1.0 op_sel_hi:[1,1,0] neg_lo:[1,0,0] neg_hi:[1,0,0]
	v_pk_fma_f32 v[130:131], v[130:131], v[134:135], 1.0 op_sel_hi:[1,1,0] neg_lo:[1,0,0] neg_hi:[1,0,0]
	v_pk_fma_f32 v[132:133], v[128:129], v[132:133], v[132:133]
	v_pk_fma_f32 v[134:135], v[130:131], v[134:135], v[134:135]
	v_pk_fma_f32 v[196:197], v[132:133], v[140:141], v[196:197]
	v_pk_fma_f32 v[198:199], v[134:135], v[142:143], v[198:199]
	global_store_dwordx4 v166, v[196:199], s[68:69]
	global_load_dwordx2 v[148:149], v167, s[58:59]
	global_load_dwordx4 v[196:199], v166, s[56:57]
	s_waitcnt vmcnt(21)
	v_pk_mul_f32 v[128:129], v[72:73], s[70:71]
	v_pk_mul_f32 v[130:131], v[74:75], s[70:71]
	v_lshlrev_b32_e32 v140, 16, v150
	v_exp_f32_e32 v128, v128
	v_exp_f32_e32 v129, v129
	v_exp_f32_e32 v130, v130
	v_exp_f32_e32 v131, v131
	v_and_b32_e32 v141, 0xffff0000, v150
	v_pk_add_f32 v[128:129], v[128:129], 1.0 op_sel_hi:[1,0]
	v_pk_add_f32 v[130:131], v[130:131], 1.0 op_sel_hi:[1,0]
	v_rcp_f32_e32 v132, v128
	v_rcp_f32_e32 v133, v129
	v_rcp_f32_e32 v134, v130
	v_rcp_f32_e32 v135, v131
	v_lshlrev_b32_e32 v142, 16, v151
	v_and_b32_e32 v143, 0xffff0000, v151
	v_pk_fma_f32 v[128:129], v[128:129], v[132:133], 1.0 op_sel_hi:[1,1,0] neg_lo:[1,0,0] neg_hi:[1,0,0]
	v_pk_fma_f32 v[130:131], v[130:131], v[134:135], 1.0 op_sel_hi:[1,1,0] neg_lo:[1,0,0] neg_hi:[1,0,0]
	v_pk_fma_f32 v[132:133], v[128:129], v[132:133], v[132:133]
	v_pk_fma_f32 v[134:135], v[130:131], v[134:135], v[134:135]
	v_pk_fma_f32 v[220:221], v[132:133], v[140:141], v[220:221]
	v_pk_fma_f32 v[222:223], v[134:135], v[142:143], v[222:223]
	global_store_dwordx4 v166, v[220:223], s[68:69] offset:64
	global_load_dwordx2 v[150:151], v167, s[58:59] offset:32
	global_load_dwordx4 v[220:223], v166, s[56:57] offset:64
	s_waitcnt vmcnt(21)
	v_pk_mul_f32 v[128:129], v[68:69], s[70:71]
	v_pk_mul_f32 v[130:131], v[70:71], s[70:71]
	v_lshlrev_b32_e32 v140, 16, v152
	v_exp_f32_e32 v128, v128
	v_exp_f32_e32 v129, v129
	v_exp_f32_e32 v130, v130
	v_exp_f32_e32 v131, v131
	v_and_b32_e32 v141, 0xffff0000, v152
	v_pk_add_f32 v[128:129], v[128:129], 1.0 op_sel_hi:[1,0]
	v_pk_add_f32 v[130:131], v[130:131], 1.0 op_sel_hi:[1,0]
	v_rcp_f32_e32 v132, v128
	v_rcp_f32_e32 v133, v129
	v_rcp_f32_e32 v134, v130
	v_rcp_f32_e32 v135, v131
	v_lshlrev_b32_e32 v142, 16, v153
	v_and_b32_e32 v143, 0xffff0000, v153
	v_pk_fma_f32 v[128:129], v[128:129], v[132:133], 1.0 op_sel_hi:[1,1,0] neg_lo:[1,0,0] neg_hi:[1,0,0]
	v_pk_fma_f32 v[130:131], v[130:131], v[134:135], 1.0 op_sel_hi:[1,1,0] neg_lo:[1,0,0] neg_hi:[1,0,0]
	v_pk_fma_f32 v[132:133], v[128:129], v[132:133], v[132:133]
	v_pk_fma_f32 v[134:135], v[130:131], v[134:135], v[134:135]
	v_pk_fma_f32 v[224:225], v[132:133], v[140:141], v[224:225]
	v_pk_fma_f32 v[226:227], v[134:135], v[142:143], v[226:227]
	global_store_dwordx4 v166, v[224:227], s[68:69] offset:512
	global_load_dwordx2 v[152:153], v167, s[58:59] offset:256
	global_load_dwordx4 v[224:227], v166, s[56:57] offset:512
	s_waitcnt vmcnt(21)
	v_pk_mul_f32 v[128:129], v[64:65], s[70:71]
	v_pk_mul_f32 v[130:131], v[66:67], s[70:71]
	v_lshlrev_b32_e32 v140, 16, v154
	v_exp_f32_e32 v128, v128
	v_exp_f32_e32 v129, v129
	v_exp_f32_e32 v130, v130
	v_exp_f32_e32 v131, v131
	v_and_b32_e32 v141, 0xffff0000, v154
	v_pk_add_f32 v[128:129], v[128:129], 1.0 op_sel_hi:[1,0]
	v_pk_add_f32 v[130:131], v[130:131], 1.0 op_sel_hi:[1,0]
	v_rcp_f32_e32 v132, v128
	v_rcp_f32_e32 v133, v129
	v_rcp_f32_e32 v134, v130
	v_rcp_f32_e32 v135, v131
	v_lshlrev_b32_e32 v142, 16, v155
	v_and_b32_e32 v143, 0xffff0000, v155
	v_pk_fma_f32 v[128:129], v[128:129], v[132:133], 1.0 op_sel_hi:[1,1,0] neg_lo:[1,0,0] neg_hi:[1,0,0]
	v_pk_fma_f32 v[130:131], v[130:131], v[134:135], 1.0 op_sel_hi:[1,1,0] neg_lo:[1,0,0] neg_hi:[1,0,0]
	v_pk_fma_f32 v[132:133], v[128:129], v[132:133], v[132:133]
	v_pk_fma_f32 v[134:135], v[130:131], v[134:135], v[134:135]
	v_pk_fma_f32 v[228:229], v[132:133], v[140:141], v[228:229]
	v_pk_fma_f32 v[230:231], v[134:135], v[142:143], v[230:231]
	global_store_dwordx4 v166, v[228:231], s[68:69] offset:576
	s_add_u32 s68, s68, 0x50000
	s_addc_u32 s69, s69, 0
	global_load_dwordx2 v[154:155], v167, s[58:59] offset:288
	global_load_dwordx4 v[228:231], v166, s[56:57] offset:576
	s_add_u32 s56, s56, 0x10000
	s_addc_u32 s57, s57, 0
	s_add_u32 s58, s58, 0x8000
	s_addc_u32 s59, s59, 0
	s_waitcnt vmcnt(21)
	v_pk_mul_f32 v[128:129], v[60:61], s[70:71]
	v_pk_mul_f32 v[130:131], v[62:63], s[70:71]
	v_lshlrev_b32_e32 v140, 16, v232
	v_exp_f32_e32 v128, v128
	v_exp_f32_e32 v129, v129
	v_exp_f32_e32 v130, v130
	v_exp_f32_e32 v131, v131
	v_and_b32_e32 v141, 0xffff0000, v232
	v_pk_add_f32 v[128:129], v[128:129], 1.0 op_sel_hi:[1,0]
	v_pk_add_f32 v[130:131], v[130:131], 1.0 op_sel_hi:[1,0]
	v_rcp_f32_e32 v132, v128
	v_rcp_f32_e32 v133, v129
	v_rcp_f32_e32 v134, v130
	v_rcp_f32_e32 v135, v131
	v_lshlrev_b32_e32 v142, 16, v233
	v_and_b32_e32 v143, 0xffff0000, v233
	v_pk_fma_f32 v[128:129], v[128:129], v[132:133], 1.0 op_sel_hi:[1,1,0] neg_lo:[1,0,0] neg_hi:[1,0,0]
	v_pk_fma_f32 v[130:131], v[130:131], v[134:135], 1.0 op_sel_hi:[1,1,0] neg_lo:[1,0,0] neg_hi:[1,0,0]
	v_pk_fma_f32 v[132:133], v[128:129], v[132:133], v[132:133]
	v_pk_fma_f32 v[134:135], v[130:131], v[134:135], v[134:135]
	v_pk_fma_f32 v[180:181], v[132:133], v[140:141], v[180:181]
	v_pk_fma_f32 v[182:183], v[134:135], v[142:143], v[182:183]
	global_store_dwordx4 v166, v[180:183], s[68:69]
	global_load_dwordx2 v[232:233], v167, s[58:59]
	global_load_dwordx4 v[180:183], v166, s[56:57]
	s_waitcnt vmcnt(21)
; DEV float bflo(unsigned w) { return __uint_as_float(w << 16); }
; DEV float bfhi(unsigned w) { return __uint_as_float(w & 0xffff0000u); }
; DEV float sigmoidf_(float x) { return 1.0f / (1.0f + __expf(-x)); }
;   DEV void operator()(const f32x4 (&acc)[2][2][4][2], const Unit& u, int wr, int wc, int fr, int fq) const {
;     const int row0 = u.pm * BM + wr * 64 + fr, col0 = u.pn * BM + wc * 32 + 4 * fq;
; #pragma unroll
;     for (int ai = 0; ai < 2; ++ai)
; #pragma unroll
;       for (int mp = 0; mp < 2; ++mp) {
;         f32x4 xv[2][2][2]; u32x2 pw[2][2][2];
; #pragma unroll
;         for (int mm = 0; mm < 2; ++mm)
; #pragma unroll
;           for (int bj = 0; bj < 2; ++bj)
; #pragma unroll
;             for (int n = 0; n < 2; ++n) {
;               const size_t o = (size_t)(row0 + ai * HALF + (mp * 2 + mm) * 16) * D + col0 + bj * HALF + n * 16;
;               pw[mm][bj][n] = *(const u32x2*)(PROJ + o);
;               xv[mm][bj][n] = *(const f32x4*)(X + o);
;             }
; #pragma unroll
;         for (int mm = 0; mm < 2; ++mm)
; #pragma unroll
;           for (int bj = 0; bj < 2; ++bj)
; #pragma unroll
;             for (int n = 0; n < 2; ++n) {
;               const size_t o = (size_t)(row0 + ai * HALF + (mp * 2 + mm) * 16) * D + col0 + bj * HALF + n * 16;
;               const f32x4 v = acc[ai][bj][mp * 2 + mm][n];
;               f32x4 x = xv[mm][bj][n]; const u32x2 w = pw[mm][bj][n];
;               x[0] += sigmoidf_(v[0]) * bflo(w.x); x[1] += sigmoidf_(v[1]) * bfhi(w.x); x[2] += sigmoidf_(v[2]) * bflo(w.y); x[3] += sigmoidf_(v[3]) * bfhi(w.y);
;               *(f32x4*)(X + o) = x;
;             }
;         asm volatile("" ::: "memory");
;       }
;   }
	v_pk_mul_f32 v[128:129], v[56:57], s[70:71]
	v_pk_mul_f32 v[130:131], v[58:59], s[70:71]
	v_lshlrev_b32_e32 v140, 16, v234
	v_exp_f32_e32 v128, v128
	v_exp_f32_e32 v129, v129
	v_exp_f32_e32 v130, v130
	v_exp_f32_e32 v131, v131
	v_and_b32_e32 v141, 0xffff0000, v234
	v_pk_add_f32 v[128:129], v[128:129], 1.0 op_sel_hi:[1,0]
	v_pk_add_f32 v[130:131], v[130:131], 1.0 op_sel_hi:[1,0]
	v_rcp_f32_e32 v132, v128
	v_rcp_f32_e32 v133, v129
	v_rcp_f32_e32 v134, v130
	v_rcp_f32_e32 v135, v131
	v_lshlrev_b32_e32 v142, 16, v235
	v_and_b32_e32 v143, 0xffff0000, v235
	v_pk_fma_f32 v[128:129], v[128:129], v[132:133], 1.0 op_sel_hi:[1,1,0] neg_lo:[1,0,0] neg_hi:[1,0,0]
	v_pk_fma_f32 v[130:131], v[130:131], v[134:135], 1.0 op_sel_hi:[1,1,0] neg_lo:[1,0,0] neg_hi:[1,0,0]
	v_pk_fma_f32 v[132:133], v[128:129], v[132:133], v[132:133]
	v_pk_fma_f32 v[134:135], v[130:131], v[134:135], v[134:135]
	v_pk_fma_f32 v[184:185], v[132:133], v[140:141], v[184:185]
	v_pk_fma_f32 v[186:187], v[134:135], v[142:143], v[186:187]
	global_store_dwordx4 v166, v[184:187], s[68:69] offset:64
	global_load_dwordx2 v[234:235], v167, s[58:59] offset:32
	global_load_dwordx4 v[184:187], v166, s[56:57] offset:64
	s_waitcnt vmcnt(21)
	v_pk_mul_f32 v[128:129], v[52:53], s[70:71]
	v_pk_mul_f32 v[130:131], v[54:55], s[70:71]
	v_lshlrev_b32_e32 v140, 16, v236
	v_exp_f32_e32 v128, v128
	v_exp_f32_e32 v129, v129
	v_exp_f32_e32 v130, v130
	v_exp_f32_e32 v131, v131
	v_and_b32_e32 v141, 0xffff0000, v236
	v_pk_add_f32 v[128:129], v[128:129], 1.0 op_sel_hi:[1,0]
	v_pk_add_f32 v[130:131], v[130:131], 1.0 op_sel_hi:[1,0]
	v_rcp_f32_e32 v132, v128
	v_rcp_f32_e32 v133, v129
	v_rcp_f32_e32 v134, v130
	v_rcp_f32_e32 v135, v131
	v_lshlrev_b32_e32 v142, 16, v237
	v_and_b32_e32 v143, 0xffff0000, v237
	v_pk_fma_f32 v[128:129], v[128:129], v[132:133], 1.0 op_sel_hi:[1,1,0] neg_lo:[1,0,0] neg_hi:[1,0,0]
	v_pk_fma_f32 v[130:131], v[130:131], v[134:135], 1.0 op_sel_hi:[1,1,0] neg_lo:[1,0,0] neg_hi:[1,0,0]
	v_pk_fma_f32 v[132:133], v[128:129], v[132:133], v[132:133]
	v_pk_fma_f32 v[134:135], v[130:131], v[134:135], v[134:135]
	v_pk_fma_f32 v[188:189], v[132:133], v[140:141], v[188:189]
	v_pk_fma_f32 v[190:191], v[134:135], v[142:143], v[190:191]
	global_store_dwordx4 v166, v[188:191], s[68:69] offset:512
	global_load_dwordx2 v[236:237], v167, s[58:59] offset:256
	global_load_dwordx4 v[188:191], v166, s[56:57] offset:512
	s_waitcnt vmcnt(21)
	v_pk_mul_f32 v[128:129], v[48:49], s[70:71]
	v_pk_mul_f32 v[130:131], v[50:51], s[70:71]
	v_lshlrev_b32_e32 v140, 16, v238
	v_exp_f32_e32 v128, v128
	v_exp_f32_e32 v129, v129
	v_exp_f32_e32 v130, v130
	v_exp_f32_e32 v131, v131
	v_and_b32_e32 v141, 0xffff0000, v238
	v_pk_add_f32 v[128:129], v[128:129], 1.0 op_sel_hi:[1,0]
	v_pk_add_f32 v[130:131], v[130:131], 1.0 op_sel_hi:[1,0]
	v_rcp_f32_e32 v132, v128
	v_rcp_f32_e32 v133, v129
	v_rcp_f32_e32 v134, v130
	v_rcp_f32_e32 v135, v131
	v_lshlrev_b32_e32 v142, 16, v239
	v_and_b32_e32 v143, 0xffff0000, v239
	v_pk_fma_f32 v[128:129], v[128:129], v[132:133], 1.0 op_sel_hi:[1,1,0] neg_lo:[1,0,0] neg_hi:[1,0,0]
	v_pk_fma_f32 v[130:131], v[130:131], v[134:135], 1.0 op_sel_hi:[1,1,0] neg_lo:[1,0,0] neg_hi:[1,0,0]
	v_pk_fma_f32 v[132:133], v[128:129], v[132:133], v[132:133]
	v_pk_fma_f32 v[134:135], v[130:131], v[134:135], v[134:135]
	v_pk_fma_f32 v[192:193], v[132:133], v[140:141], v[192:193]
	v_pk_fma_f32 v[194:195], v[134:135], v[142:143], v[194:195]
	global_store_dwordx4 v166, v[192:195], s[68:69] offset:576
	s_add_u32 s68, s68, 0x10000
	s_addc_u32 s69, s69, 0
	global_load_dwordx2 v[238:239], v167, s[58:59] offset:288
	global_load_dwordx4 v[192:195], v166, s[56:57] offset:576
	s_add_u32 s56, s56, 0x10000
	s_addc_u32 s57, s57, 0
	s_add_u32 s58, s58, 0x8000
	s_addc_u32 s59, s59, 0
	s_waitcnt vmcnt(21)
	v_pk_mul_f32 v[128:129], v[44:45], s[70:71]
	v_pk_mul_f32 v[130:131], v[46:47], s[70:71]
	v_lshlrev_b32_e32 v140, 16, v148
	v_exp_f32_e32 v128, v128
	v_exp_f32_e32 v129, v129
	v_exp_f32_e32 v130, v130
	v_exp_f32_e32 v131, v131
	v_and_b32_e32 v141, 0xffff0000, v148
	v_pk_add_f32 v[128:129], v[128:129], 1.0 op_sel_hi:[1,0]
	v_pk_add_f32 v[130:131], v[130:131], 1.0 op_sel_hi:[1,0]
	v_rcp_f32_e32 v132, v128
	v_rcp_f32_e32 v133, v129
	v_rcp_f32_e32 v134, v130
	v_rcp_f32_e32 v135, v131
	v_lshlrev_b32_e32 v142, 16, v149
	v_and_b32_e32 v143, 0xffff0000, v149
	v_pk_fma_f32 v[128:129], v[128:129], v[132:133], 1.0 op_sel_hi:[1,1,0] neg_lo:[1,0,0] neg_hi:[1,0,0]
	v_pk_fma_f32 v[130:131], v[130:131], v[134:135], 1.0 op_sel_hi:[1,1,0] neg_lo:[1,0,0] neg_hi:[1,0,0]
	v_pk_fma_f32 v[132:133], v[128:129], v[132:133], v[132:133]
	v_pk_fma_f32 v[134:135], v[130:131], v[134:135], v[134:135]
	v_pk_fma_f32 v[196:197], v[132:133], v[140:141], v[196:197]
	v_pk_fma_f32 v[198:199], v[134:135], v[142:143], v[198:199]
	global_store_dwordx4 v166, v[196:199], s[68:69]
	global_load_dwordx2 v[148:149], v167, s[58:59]
	global_load_dwordx4 v[196:199], v166, s[56:57]
	s_waitcnt vmcnt(21)
	v_pk_mul_f32 v[128:129], v[40:41], s[70:71]
	v_pk_mul_f32 v[130:131], v[42:43], s[70:71]
	v_lshlrev_b32_e32 v140, 16, v150
	v_exp_f32_e32 v128, v128
	v_exp_f32_e32 v129, v129
	v_exp_f32_e32 v130, v130
	v_exp_f32_e32 v131, v131
	v_and_b32_e32 v141, 0xffff0000, v150
	v_pk_add_f32 v[128:129], v[128:129], 1.0 op_sel_hi:[1,0]
	v_pk_add_f32 v[130:131], v[130:131], 1.0 op_sel_hi:[1,0]
	v_rcp_f32_e32 v132, v128
	v_rcp_f32_e32 v133, v129
	v_rcp_f32_e32 v134, v130
	v_rcp_f32_e32 v135, v131
	v_lshlrev_b32_e32 v142, 16, v151
	v_and_b32_e32 v143, 0xffff0000, v151
	v_pk_fma_f32 v[128:129], v[128:129], v[132:133], 1.0 op_sel_hi:[1,1,0] neg_lo:[1,0,0] neg_hi:[1,0,0]
	v_pk_fma_f32 v[130:131], v[130:131], v[134:135], 1.0 op_sel_hi:[1,1,0] neg_lo:[1,0,0] neg_hi:[1,0,0]
	v_pk_fma_f32 v[132:133], v[128:129], v[132:133], v[132:133]
	v_pk_fma_f32 v[134:135], v[130:131], v[134:135], v[134:135]
	v_pk_fma_f32 v[220:221], v[132:133], v[140:141], v[220:221]
	v_pk_fma_f32 v[222:223], v[134:135], v[142:143], v[222:223]
	global_store_dwordx4 v166, v[220:223], s[68:69] offset:64
	global_load_dwordx2 v[150:151], v167, s[58:59] offset:32
	global_load_dwordx4 v[220:223], v166, s[56:57] offset:64
	s_waitcnt vmcnt(21)
; DEV float bflo(unsigned w) { return __uint_as_float(w << 16); }
; DEV float bfhi(unsigned w) { return __uint_as_float(w & 0xffff0000u); }
; DEV float sigmoidf_(float x) { return 1.0f / (1.0f + __expf(-x)); }
;   DEV void operator()(const f32x4 (&acc)[2][2][4][2], const Unit& u, int wr, int wc, int fr, int fq) const {
;     const int row0 = u.pm * BM + wr * 64 + fr, col0 = u.pn * BM + wc * 32 + 4 * fq;
; #pragma unroll
;     for (int ai = 0; ai < 2; ++ai)
; #pragma unroll
;       for (int mp = 0; mp < 2; ++mp) {
;         f32x4 xv[2][2][2]; u32x2 pw[2][2][2];
; #pragma unroll
;         for (int mm = 0; mm < 2; ++mm)
; #pragma unroll
;           for (int bj = 0; bj < 2; ++bj)
; #pragma unroll
;             for (int n = 0; n < 2; ++n) {
;               const size_t o = (size_t)(row0 + ai * HALF + (mp * 2 + mm) * 16) * D + col0 + bj * HALF + n * 16;
;               pw[mm][bj][n] = *(const u32x2*)(PROJ + o);
;               xv[mm][bj][n] = *(const f32x4*)(X + o);
;             }
; #pragma unroll
;         for (int mm = 0; mm < 2; ++mm)
; #pragma unroll
;           for (int bj = 0; bj < 2; ++bj)
; #pragma unroll
;             for (int n = 0; n < 2; ++n) {
;               const size_t o = (size_t)(row0 + ai * HALF + (mp * 2 + mm) * 16) * D + col0 + bj * HALF + n * 16;
;               const f32x4 v = acc[ai][bj][mp * 2 + mm][n];
;               f32x4 x = xv[mm][bj][n]; const u32x2 w = pw[mm][bj][n];
;               x[0] += sigmoidf_(v[0]) * bflo(w.x); x[1] += sigmoidf_(v[1]) * bfhi(w.x); x[2] += sigmoidf_(v[2]) * bflo(w.y); x[3] += sigmoidf_(v[3]) * bfhi(w.y);
;               *(f32x4*)(X + o) = x;
;             }
;         asm volatile("" ::: "memory");
;       }
;   }
	v_pk_mul_f32 v[128:129], v[36:37], s[70:71]
	v_pk_mul_f32 v[130:131], v[38:39], s[70:71]
	v_lshlrev_b32_e32 v140, 16, v152
	v_exp_f32_e32 v128, v128
	v_exp_f32_e32 v129, v129
	v_exp_f32_e32 v130, v130
	v_exp_f32_e32 v131, v131
	v_and_b32_e32 v141, 0xffff0000, v152
	v_pk_add_f32 v[128:129], v[128:129], 1.0 op_sel_hi:[1,0]
	v_pk_add_f32 v[130:131], v[130:131], 1.0 op_sel_hi:[1,0]
	v_rcp_f32_e32 v132, v128
	v_rcp_f32_e32 v133, v129
	v_rcp_f32_e32 v134, v130
	v_rcp_f32_e32 v135, v131
	v_lshlrev_b32_e32 v142, 16, v153
	v_and_b32_e32 v143, 0xffff0000, v153
	v_pk_fma_f32 v[128:129], v[128:129], v[132:133], 1.0 op_sel_hi:[1,1,0] neg_lo:[1,0,0] neg_hi:[1,0,0]
	v_pk_fma_f32 v[130:131], v[130:131], v[134:135], 1.0 op_sel_hi:[1,1,0] neg_lo:[1,0,0] neg_hi:[1,0,0]
	v_pk_fma_f32 v[132:133], v[128:129], v[132:133], v[132:133]
	v_pk_fma_f32 v[134:135], v[130:131], v[134:135], v[134:135]
	v_pk_fma_f32 v[224:225], v[132:133], v[140:141], v[224:225]
	v_pk_fma_f32 v[226:227], v[134:135], v[142:143], v[226:227]
	global_store_dwordx4 v166, v[224:227], s[68:69] offset:512
	global_load_dwordx2 v[152:153], v167, s[58:59] offset:256
	global_load_dwordx4 v[224:227], v166, s[56:57] offset:512
	s_waitcnt vmcnt(21)
	v_pk_mul_f32 v[128:129], v[32:33], s[70:71]
	v_pk_mul_f32 v[130:131], v[34:35], s[70:71]
	v_lshlrev_b32_e32 v140, 16, v154
	v_exp_f32_e32 v128, v128
	v_exp_f32_e32 v129, v129
	v_exp_f32_e32 v130, v130
	v_exp_f32_e32 v131, v131
	v_and_b32_e32 v141, 0xffff0000, v154
	v_pk_add_f32 v[128:129], v[128:129], 1.0 op_sel_hi:[1,0]
	v_pk_add_f32 v[130:131], v[130:131], 1.0 op_sel_hi:[1,0]
	v_rcp_f32_e32 v132, v128
	v_rcp_f32_e32 v133, v129
	v_rcp_f32_e32 v134, v130
	v_rcp_f32_e32 v135, v131
	v_lshlrev_b32_e32 v142, 16, v155
	v_and_b32_e32 v143, 0xffff0000, v155
	v_pk_fma_f32 v[128:129], v[128:129], v[132:133], 1.0 op_sel_hi:[1,1,0] neg_lo:[1,0,0] neg_hi:[1,0,0]
	v_pk_fma_f32 v[130:131], v[130:131], v[134:135], 1.0 op_sel_hi:[1,1,0] neg_lo:[1,0,0] neg_hi:[1,0,0]
	v_pk_fma_f32 v[132:133], v[128:129], v[132:133], v[132:133]
	v_pk_fma_f32 v[134:135], v[130:131], v[134:135], v[134:135]
	v_pk_fma_f32 v[228:229], v[132:133], v[140:141], v[228:229]
	v_pk_fma_f32 v[230:231], v[134:135], v[142:143], v[230:231]
	global_store_dwordx4 v166, v[228:231], s[68:69] offset:576
	s_add_u32 s68, s68, 0x10000
	s_addc_u32 s69, s69, 0
	global_load_dwordx2 v[154:155], v167, s[58:59] offset:288
	global_load_dwordx4 v[228:231], v166, s[56:57] offset:576
	s_waitcnt vmcnt(21)
	v_pk_mul_f32 v[128:129], v[28:29], s[70:71]
	v_pk_mul_f32 v[130:131], v[30:31], s[70:71]
	v_lshlrev_b32_e32 v140, 16, v232
	v_exp_f32_e32 v128, v128
	v_exp_f32_e32 v129, v129
	v_exp_f32_e32 v130, v130
	v_exp_f32_e32 v131, v131
	v_and_b32_e32 v141, 0xffff0000, v232
	v_pk_add_f32 v[128:129], v[128:129], 1.0 op_sel_hi:[1,0]
	v_pk_add_f32 v[130:131], v[130:131], 1.0 op_sel_hi:[1,0]
	v_rcp_f32_e32 v132, v128
	v_rcp_f32_e32 v133, v129
	v_rcp_f32_e32 v134, v130
	v_rcp_f32_e32 v135, v131
	v_lshlrev_b32_e32 v142, 16, v233
	v_and_b32_e32 v143, 0xffff0000, v233
	v_pk_fma_f32 v[128:129], v[128:129], v[132:133], 1.0 op_sel_hi:[1,1,0] neg_lo:[1,0,0] neg_hi:[1,0,0]
	v_pk_fma_f32 v[130:131], v[130:131], v[134:135], 1.0 op_sel_hi:[1,1,0] neg_lo:[1,0,0] neg_hi:[1,0,0]
	v_pk_fma_f32 v[132:133], v[128:129], v[132:133], v[132:133]
	v_pk_fma_f32 v[134:135], v[130:131], v[134:135], v[134:135]
	v_pk_fma_f32 v[180:181], v[132:133], v[140:141], v[180:181]
	v_pk_fma_f32 v[182:183], v[134:135], v[142:143], v[182:183]
	global_store_dwordx4 v166, v[180:183], s[68:69]
	s_waitcnt vmcnt(19)
	v_pk_mul_f32 v[128:129], v[24:25], s[70:71]
	v_pk_mul_f32 v[130:131], v[26:27], s[70:71]
	v_lshlrev_b32_e32 v140, 16, v234
	v_exp_f32_e32 v128, v128
	v_exp_f32_e32 v129, v129
	v_exp_f32_e32 v130, v130
	v_exp_f32_e32 v131, v131
	v_and_b32_e32 v141, 0xffff0000, v234
	v_pk_add_f32 v[128:129], v[128:129], 1.0 op_sel_hi:[1,0]
	v_pk_add_f32 v[130:131], v[130:131], 1.0 op_sel_hi:[1,0]
	v_rcp_f32_e32 v132, v128
	v_rcp_f32_e32 v133, v129
	v_rcp_f32_e32 v134, v130
	v_rcp_f32_e32 v135, v131
	v_lshlrev_b32_e32 v142, 16, v235
	v_and_b32_e32 v143, 0xffff0000, v235
	v_pk_fma_f32 v[128:129], v[128:129], v[132:133], 1.0 op_sel_hi:[1,1,0] neg_lo:[1,0,0] neg_hi:[1,0,0]
	v_pk_fma_f32 v[130:131], v[130:131], v[134:135], 1.0 op_sel_hi:[1,1,0] neg_lo:[1,0,0] neg_hi:[1,0,0]
	v_pk_fma_f32 v[132:133], v[128:129], v[132:133], v[132:133]
	v_pk_fma_f32 v[134:135], v[130:131], v[134:135], v[134:135]
	v_pk_fma_f32 v[184:185], v[132:133], v[140:141], v[184:185]
	v_pk_fma_f32 v[186:187], v[134:135], v[142:143], v[186:187]
	global_store_dwordx4 v166, v[184:187], s[68:69] offset:64
	s_waitcnt vmcnt(17)
	v_pk_mul_f32 v[128:129], v[20:21], s[70:71]
	v_pk_mul_f32 v[130:131], v[22:23], s[70:71]
	v_lshlrev_b32_e32 v140, 16, v236
	v_exp_f32_e32 v128, v128
	v_exp_f32_e32 v129, v129
	v_exp_f32_e32 v130, v130
	v_exp_f32_e32 v131, v131
	v_and_b32_e32 v141, 0xffff0000, v236
	v_pk_add_f32 v[128:129], v[128:129], 1.0 op_sel_hi:[1,0]
	v_pk_add_f32 v[130:131], v[130:131], 1.0 op_sel_hi:[1,0]
	v_rcp_f32_e32 v132, v128
	v_rcp_f32_e32 v133, v129
	v_rcp_f32_e32 v134, v130
	v_rcp_f32_e32 v135, v131
	v_lshlrev_b32_e32 v142, 16, v237
	v_and_b32_e32 v143, 0xffff0000, v237
	v_pk_fma_f32 v[128:129], v[128:129], v[132:133], 1.0 op_sel_hi:[1,1,0] neg_lo:[1,0,0] neg_hi:[1,0,0]
	v_pk_fma_f32 v[130:131], v[130:131], v[134:135], 1.0 op_sel_hi:[1,1,0] neg_lo:[1,0,0] neg_hi:[1,0,0]
	v_pk_fma_f32 v[132:133], v[128:129], v[132:133], v[132:133]
	v_pk_fma_f32 v[134:135], v[130:131], v[134:135], v[134:135]
	v_pk_fma_f32 v[188:189], v[132:133], v[140:141], v[188:189]
	v_pk_fma_f32 v[190:191], v[134:135], v[142:143], v[190:191]
	global_store_dwordx4 v166, v[188:191], s[68:69] offset:512
	s_waitcnt vmcnt(15)
; DEV float bflo(unsigned w) { return __uint_as_float(w << 16); }
; DEV float bfhi(unsigned w) { return __uint_as_float(w & 0xffff0000u); }
; DEV float sigmoidf_(float x) { return 1.0f / (1.0f + __expf(-x)); }
; #define PG8_BAR __builtin_amdgcn_s_barrier()
; template <class Epi, bool SEQ>
; DEV void gemm_phase(PG8_LAS unsigned char* lds, const Gemm g, const Epi& E) {
;     ...
;     if (!keep) E(acc, cur, wr, wc, fr, fq);
;     if (!has_next) break;
;     if (!keep) {
; #pragma unroll
;       for (int a = 0; a < 2; ++a)
; #pragma unroll
;         for (int b = 0; b < 2; ++b)
; #pragma unroll
;           for (int m = 0; m < 4; ++m)
; #pragma unroll
;             for (int n = 0; n < 2; ++n) acc[a][b][m][n] = (f32x4){0.f, 0.f, 0.f, 0.f};
;     }
;     cur = nxt; cA = nA; cB = nB; ++ui;
;     if (wr == 1) PG8_BAR;
;   }
;   DEV void operator()(const f32x4 (&acc)[2][2][4][2], const Unit& u, int wr, int wc, int fr, int fq) const {
;     const int row0 = u.pm * BM + wr * 64 + fr, col0 = u.pn * BM + wc * 32 + 4 * fq;
; #pragma unroll
;     for (int ai = 0; ai < 2; ++ai)
; #pragma unroll
;       for (int mp = 0; mp < 2; ++mp) {
;         f32x4 xv[2][2][2]; u32x2 pw[2][2][2];
; #pragma unroll
;         for (int mm = 0; mm < 2; ++mm)
; #pragma unroll
;           for (int bj = 0; bj < 2; ++bj)
; #pragma unroll
;             for (int n = 0; n < 2; ++n) {
;               const size_t o = (size_t)(row0 + ai * HALF + (mp * 2 + mm) * 16) * D + col0 + bj * HALF + n * 16;
;               pw[mm][bj][n] = *(const u32x2*)(PROJ + o);
;               xv[mm][bj][n] = *(const f32x4*)(X + o);
;             }
; #pragma unroll
;         for (int mm = 0; mm < 2; ++mm)
; #pragma unroll
;           for (int bj = 0; bj < 2; ++bj)
; #pragma unroll
;             for (int n = 0; n < 2; ++n) {
;               const size_t o = (size_t)(row0 + ai * HALF + (mp * 2 + mm) * 16) * D + col0 + bj * HALF + n * 16;
;               const f32x4 v = acc[ai][bj][mp * 2 + mm][n];
;               f32x4 x = xv[mm][bj][n]; const u32x2 w = pw[mm][bj][n];
;               x[0] += sigmoidf_(v[0]) * bflo(w.x); x[1] += sigmoidf_(v[1]) * bfhi(w.x); x[2] += sigmoidf_(v[2]) * bflo(w.y); x[3] += sigmoidf_(v[3]) * bfhi(w.y);
;               *(f32x4*)(X + o) = x;
;             }
;         asm volatile("" ::: "memory");
;       }
;   }
	v_pk_mul_f32 v[128:129], v[16:17], s[70:71]
	v_pk_mul_f32 v[130:131], v[18:19], s[70:71]
	v_lshlrev_b32_e32 v140, 16, v238
	v_exp_f32_e32 v128, v128
	v_exp_f32_e32 v129, v129
	v_exp_f32_e32 v130, v130
	v_exp_f32_e32 v131, v131
	v_and_b32_e32 v141, 0xffff0000, v238
	v_pk_add_f32 v[128:129], v[128:129], 1.0 op_sel_hi:[1,0]
	v_pk_add_f32 v[130:131], v[130:131], 1.0 op_sel_hi:[1,0]
	v_rcp_f32_e32 v132, v128
	v_rcp_f32_e32 v133, v129
	v_rcp_f32_e32 v134, v130
	v_rcp_f32_e32 v135, v131
	v_lshlrev_b32_e32 v142, 16, v239
	v_and_b32_e32 v143, 0xffff0000, v239
	v_pk_fma_f32 v[128:129], v[128:129], v[132:133], 1.0 op_sel_hi:[1,1,0] neg_lo:[1,0,0] neg_hi:[1,0,0]
	v_pk_fma_f32 v[130:131], v[130:131], v[134:135], 1.0 op_sel_hi:[1,1,0] neg_lo:[1,0,0] neg_hi:[1,0,0]
	v_pk_fma_f32 v[132:133], v[128:129], v[132:133], v[132:133]
	v_pk_fma_f32 v[134:135], v[130:131], v[134:135], v[134:135]
	v_pk_fma_f32 v[192:193], v[132:133], v[140:141], v[192:193]
	v_pk_fma_f32 v[194:195], v[134:135], v[142:143], v[194:195]
	global_store_dwordx4 v166, v[192:195], s[68:69] offset:576
	s_add_u32 s68, s68, 0x10000
	s_addc_u32 s69, s69, 0
	s_waitcnt vmcnt(13)
	v_pk_mul_f32 v[128:129], v[12:13], s[70:71]
	v_pk_mul_f32 v[130:131], v[14:15], s[70:71]
	v_lshlrev_b32_e32 v140, 16, v148
	v_exp_f32_e32 v128, v128
	v_exp_f32_e32 v129, v129
	v_exp_f32_e32 v130, v130
	v_exp_f32_e32 v131, v131
	v_and_b32_e32 v141, 0xffff0000, v148
	v_pk_add_f32 v[128:129], v[128:129], 1.0 op_sel_hi:[1,0]
	v_pk_add_f32 v[130:131], v[130:131], 1.0 op_sel_hi:[1,0]
	v_rcp_f32_e32 v132, v128
	v_rcp_f32_e32 v133, v129
	v_rcp_f32_e32 v134, v130
	v_rcp_f32_e32 v135, v131
	v_lshlrev_b32_e32 v142, 16, v149
	v_and_b32_e32 v143, 0xffff0000, v149
	v_pk_fma_f32 v[128:129], v[128:129], v[132:133], 1.0 op_sel_hi:[1,1,0] neg_lo:[1,0,0] neg_hi:[1,0,0]
	v_pk_fma_f32 v[130:131], v[130:131], v[134:135], 1.0 op_sel_hi:[1,1,0] neg_lo:[1,0,0] neg_hi:[1,0,0]
	v_pk_fma_f32 v[132:133], v[128:129], v[132:133], v[132:133]
	v_pk_fma_f32 v[134:135], v[130:131], v[134:135], v[134:135]
	v_pk_fma_f32 v[196:197], v[132:133], v[140:141], v[196:197]
	v_pk_fma_f32 v[198:199], v[134:135], v[142:143], v[198:199]
	global_store_dwordx4 v166, v[196:199], s[68:69]
	s_waitcnt vmcnt(11)
	v_pk_mul_f32 v[128:129], v[8:9], s[70:71]
	v_pk_mul_f32 v[130:131], v[10:11], s[70:71]
	v_lshlrev_b32_e32 v140, 16, v150
	v_exp_f32_e32 v128, v128
	v_exp_f32_e32 v129, v129
	v_exp_f32_e32 v130, v130
	v_exp_f32_e32 v131, v131
	v_and_b32_e32 v141, 0xffff0000, v150
	v_pk_add_f32 v[128:129], v[128:129], 1.0 op_sel_hi:[1,0]
	v_pk_add_f32 v[130:131], v[130:131], 1.0 op_sel_hi:[1,0]
	v_rcp_f32_e32 v132, v128
	v_rcp_f32_e32 v133, v129
	v_rcp_f32_e32 v134, v130
	v_rcp_f32_e32 v135, v131
	v_lshlrev_b32_e32 v142, 16, v151
	v_and_b32_e32 v143, 0xffff0000, v151
	v_pk_fma_f32 v[128:129], v[128:129], v[132:133], 1.0 op_sel_hi:[1,1,0] neg_lo:[1,0,0] neg_hi:[1,0,0]
	v_pk_fma_f32 v[130:131], v[130:131], v[134:135], 1.0 op_sel_hi:[1,1,0] neg_lo:[1,0,0] neg_hi:[1,0,0]
	v_pk_fma_f32 v[132:133], v[128:129], v[132:133], v[132:133]
	v_pk_fma_f32 v[134:135], v[130:131], v[134:135], v[134:135]
	v_pk_fma_f32 v[220:221], v[132:133], v[140:141], v[220:221]
	v_pk_fma_f32 v[222:223], v[134:135], v[142:143], v[222:223]
	global_store_dwordx4 v166, v[220:223], s[68:69] offset:64
	s_waitcnt vmcnt(9)
	v_pk_mul_f32 v[128:129], v[4:5], s[70:71]
	v_pk_mul_f32 v[130:131], v[6:7], s[70:71]
	v_lshlrev_b32_e32 v140, 16, v152
	v_exp_f32_e32 v128, v128
	v_exp_f32_e32 v129, v129
	v_exp_f32_e32 v130, v130
	v_exp_f32_e32 v131, v131
	v_and_b32_e32 v141, 0xffff0000, v152
	v_pk_add_f32 v[128:129], v[128:129], 1.0 op_sel_hi:[1,0]
	v_pk_add_f32 v[130:131], v[130:131], 1.0 op_sel_hi:[1,0]
	v_rcp_f32_e32 v132, v128
	v_rcp_f32_e32 v133, v129
	v_rcp_f32_e32 v134, v130
	v_rcp_f32_e32 v135, v131
	v_lshlrev_b32_e32 v142, 16, v153
	v_and_b32_e32 v143, 0xffff0000, v153
	v_pk_fma_f32 v[128:129], v[128:129], v[132:133], 1.0 op_sel_hi:[1,1,0] neg_lo:[1,0,0] neg_hi:[1,0,0]
	v_pk_fma_f32 v[130:131], v[130:131], v[134:135], 1.0 op_sel_hi:[1,1,0] neg_lo:[1,0,0] neg_hi:[1,0,0]
	v_pk_fma_f32 v[132:133], v[128:129], v[132:133], v[132:133]
	v_pk_fma_f32 v[134:135], v[130:131], v[134:135], v[134:135]
	v_pk_fma_f32 v[224:225], v[132:133], v[140:141], v[224:225]
	v_pk_fma_f32 v[226:227], v[134:135], v[142:143], v[226:227]
	global_store_dwordx4 v166, v[224:227], s[68:69] offset:512
	s_waitcnt vmcnt(7)
	v_pk_mul_f32 v[128:129], v[0:1], s[70:71]
	v_pk_mul_f32 v[130:131], v[2:3], s[70:71]
	v_lshlrev_b32_e32 v140, 16, v154
	v_exp_f32_e32 v128, v128
	v_exp_f32_e32 v129, v129
	v_exp_f32_e32 v130, v130
	v_exp_f32_e32 v131, v131
	v_and_b32_e32 v141, 0xffff0000, v154
	v_pk_add_f32 v[128:129], v[128:129], 1.0 op_sel_hi:[1,0]
	v_pk_add_f32 v[130:131], v[130:131], 1.0 op_sel_hi:[1,0]
	v_rcp_f32_e32 v132, v128
	v_rcp_f32_e32 v133, v129
	v_rcp_f32_e32 v134, v130
	v_rcp_f32_e32 v135, v131
	v_lshlrev_b32_e32 v142, 16, v155
	v_and_b32_e32 v143, 0xffff0000, v155
	v_pk_fma_f32 v[128:129], v[128:129], v[132:133], 1.0 op_sel_hi:[1,1,0] neg_lo:[1,0,0] neg_hi:[1,0,0]
	v_pk_fma_f32 v[130:131], v[130:131], v[134:135], 1.0 op_sel_hi:[1,1,0] neg_lo:[1,0,0] neg_hi:[1,0,0]
	v_pk_fma_f32 v[132:133], v[128:129], v[132:133], v[132:133]
	v_pk_fma_f32 v[134:135], v[130:131], v[134:135], v[134:135]
	v_pk_fma_f32 v[228:229], v[132:133], v[140:141], v[228:229]
	v_pk_fma_f32 v[230:231], v[134:135], v[142:143], v[230:231]
	global_store_dwordx4 v166, v[228:231], s[68:69] offset:576
	s_mov_b64 s[2:3], -1
	s_andn2_b64 vcc, exec, s[62:63]
	s_cbranch_vccnz .LBB0_122
	s_andn2_b64 vcc, exec, s[54:55]
	s_cbranch_vccnz .LBB0_121
	s_barrier
	s_branch .LBB0_121

; DEV unsigned cvt_pk_bf16(float lo, float hi) { const f32x2_ v = {lo, hi}; return __builtin_bit_cast(unsigned, __builtin_convertvector(v, bf16x2n_)); }
; DEV float bflo(unsigned w) { return __uint_as_float(w << 16); }
; DEV float bfhi(unsigned w) { return __uint_as_float(w & 0xffff0000u); }
;   DEV bool rescale(f32x4 (&acc)[2][2][4][2], const Unit& u, int wr, int wc, int fr, int fq) const {
;     const int row0 = u.pm * BM + wr * 64 + fr, col0 = u.pn * BM + wc * 32 + 8 * fq;
;     const bool lastseg = u.seg == 2;
;     const int sb = lastseg ? 2 : u.seg + 1;
;     const float one = lastseg ? 0.f : 1.f;
; #pragma unroll
;     for (int ai = 0; ai < 2; ++ai)
; #pragma unroll
;       for (int m = 0; m < 4; ++m) {
;         const size_t r = (size_t)(row0 + ai * HALF + m * 16);
; #pragma unroll
;         for (int bj = 0; bj < 2; ++bj) {
;           const int c = col0 + bj * HALF;
;           const u32x4 ga = *(const u32x4*)(Z + r * NIN + GT + u.seg * D + c);
;           const u32x4 gb = *(const u32x4*)(Z + r * NIN + GT + sb * D + c);
;     ...
;           acc[ai][bj][m][0][0] *= RS_(bflo(ga.x), bflo(gb.x)); acc[ai][bj][m][0][1] *= RS_(bfhi(ga.x), bfhi(gb.x));
;           acc[ai][bj][m][0][2] *= RS_(bflo(ga.y), bflo(gb.y)); acc[ai][bj][m][0][3] *= RS_(bfhi(ga.y), bfhi(gb.y));
;           acc[ai][bj][m][1][0] *= RS_(bflo(ga.z), bflo(gb.z)); acc[ai][bj][m][1][1] *= RS_(bfhi(ga.z), bfhi(gb.z));
;           acc[ai][bj][m][1][2] *= RS_(bflo(ga.w), bflo(gb.w)); acc[ai][bj][m][1][3] *= RS_(bfhi(ga.w), bfhi(gb.w));
;     ...
;           asm volatile("" ::: "memory");
;         }
;       }
;     return !lastseg;
;   }
;   DEV void operator()(const f32x4 (&acc)[2][2][4][2], const Unit& u, int wr, int wc, int fr, int fq) const {
;     const int row0 = u.pm * BM + wr * 64 + fr, col0 = u.pn * BM + wc * 32 + 8 * fq;
; #pragma unroll
;     for (int ai = 0; ai < 2; ++ai)
; #pragma unroll
;       for (int m = 0; m < 4; ++m) {
;         bf16_t* rowp = H + (size_t)(row0 + ai * HALF + m * 16) * D + col0;
; #pragma unroll
;         for (int bj = 0; bj < 2; ++bj) {
;           const f32x4 v0 = acc[ai][bj][m][0], v1 = acc[ai][bj][m][1];
;           u32x4 w; w.x = cvt_pk_bf16(v0[0], v0[1]); w.y = cvt_pk_bf16(v0[2], v0[3]); w.z = cvt_pk_bf16(v1[0], v1[1]); w.w = cvt_pk_bf16(v1[2], v1[3]);
;           *(u32x4*)(rowp + bj * HALF) = w;
;         }
;       }
;   }
.Lp4epi_last:
	v_lshlrev_b32_e32 v144, 11, v144
	s_mov_b32 s18, 0xbfb8aa3b
	s_mov_b32 s19, 0xbfb8aa3b
	s_mov_b64 s[50:51], s[24:25]
	v_add_u32_e32 v144, v144, v145
	global_load_dwordx4 v[180:183], v[218:219], off
	global_load_dwordx4 v[184:187], v[218:219], off offset:256
	v_lshl_add_u64 v[218:219], v[218:219], 0, s[20:21]
	global_load_dwordx4 v[196:199], v[218:219], off
	global_load_dwordx4 v[220:223], v[218:219], off offset:256
	v_lshl_add_u64 v[218:219], v[218:219], 0, s[20:21]
	global_load_dwordx4 v[232:235], v[218:219], off
	global_load_dwordx4 v[236:239], v[218:219], off offset:256
	v_lshl_add_u64 v[218:219], v[218:219], 0, s[20:21]
	s_waitcnt vmcnt(4)
	v_lshlrev_b32_e32 v128, 16, v180
	v_and_b32_e32 v129, 0xffff0000, v180
	v_lshlrev_b32_e32 v130, 16, v181
	v_and_b32_e32 v131, 0xffff0000, v181
	v_lshlrev_b32_e32 v152, 16, v182
	v_and_b32_e32 v153, 0xffff0000, v182
	v_lshlrev_b32_e32 v154, 16, v183
	v_and_b32_e32 v155, 0xffff0000, v183
	v_pk_mul_f32 v[128:129], v[128:129], s[18:19]
	v_pk_mul_f32 v[130:131], v[130:131], s[18:19]
	v_pk_mul_f32 v[152:153], v[152:153], s[18:19]
	v_pk_mul_f32 v[154:155], v[154:155], s[18:19]
	v_exp_f32_e32 v128, v128
	v_exp_f32_e32 v129, v129
	v_exp_f32_e32 v130, v130
	v_exp_f32_e32 v131, v131
	v_exp_f32_e32 v152, v152
	v_exp_f32_e32 v153, v153
	v_exp_f32_e32 v154, v154
	v_exp_f32_e32 v155, v155
	v_pk_add_f32 v[128:129], v[128:129], 1.0 op_sel_hi:[1,0]
	v_pk_add_f32 v[130:131], v[130:131], 1.0 op_sel_hi:[1,0]
	v_pk_add_f32 v[152:153], v[152:153], 1.0 op_sel_hi:[1,0]
	v_pk_add_f32 v[154:155], v[154:155], 1.0 op_sel_hi:[1,0]
	v_rcp_f32_e32 v128, v128
	v_rcp_f32_e32 v129, v129
	v_rcp_f32_e32 v130, v130
	v_rcp_f32_e32 v131, v131
	v_rcp_f32_e32 v152, v152
	v_rcp_f32_e32 v153, v153
	v_rcp_f32_e32 v154, v154
	v_rcp_f32_e32 v155, v155
	v_pk_mul_f32 v[124:125], v[124:125], v[128:129]
	v_pk_mul_f32 v[126:127], v[126:127], v[130:131]
	v_pk_mul_f32 v[120:121], v[120:121], v[152:153]
	v_pk_mul_f32 v[122:123], v[122:123], v[154:155]
	v_lshlrev_b32_e32 v128, 16, v184
	v_and_b32_e32 v129, 0xffff0000, v184
	v_lshlrev_b32_e32 v130, 16, v185
	v_and_b32_e32 v131, 0xffff0000, v185
	v_lshlrev_b32_e32 v152, 16, v186
	v_and_b32_e32 v153, 0xffff0000, v186
	v_lshlrev_b32_e32 v154, 16, v187
	v_and_b32_e32 v155, 0xffff0000, v187
	v_pk_mul_f32 v[128:129], v[128:129], s[18:19]
	v_pk_mul_f32 v[130:131], v[130:131], s[18:19]
	v_pk_mul_f32 v[152:153], v[152:153], s[18:19]
	v_pk_mul_f32 v[154:155], v[154:155], s[18:19]
	v_exp_f32_e32 v128, v128
	v_exp_f32_e32 v129, v129
	v_exp_f32_e32 v130, v130
	v_exp_f32_e32 v131, v131
	v_exp_f32_e32 v152, v152
	v_exp_f32_e32 v153, v153
	v_exp_f32_e32 v154, v154
	v_exp_f32_e32 v155, v155
	v_pk_add_f32 v[128:129], v[128:129], 1.0 op_sel_hi:[1,0]
	v_pk_add_f32 v[130:131], v[130:131], 1.0 op_sel_hi:[1,0]
	v_pk_add_f32 v[152:153], v[152:153], 1.0 op_sel_hi:[1,0]
	v_pk_add_f32 v[154:155], v[154:155], 1.0 op_sel_hi:[1,0]
	v_rcp_f32_e32 v128, v128
	v_rcp_f32_e32 v129, v129
	v_rcp_f32_e32 v130, v130
	v_rcp_f32_e32 v131, v131
	v_rcp_f32_e32 v152, v152
	v_rcp_f32_e32 v153, v153
	v_rcp_f32_e32 v154, v154
	v_rcp_f32_e32 v155, v155
	v_pk_mul_f32 v[92:93], v[92:93], v[128:129]
	v_pk_mul_f32 v[94:95], v[94:95], v[130:131]
	v_pk_mul_f32 v[88:89], v[88:89], v[152:153]
	v_pk_mul_f32 v[90:91], v[90:91], v[154:155]
	v_cvt_pk_bf16_f32 v180, v124, v125
	v_cvt_pk_bf16_f32 v181, v126, v127
	v_cvt_pk_bf16_f32 v182, v120, v121
	v_cvt_pk_bf16_f32 v183, v122, v123
	global_store_dwordx4 v144, v[180:183], s[50:51]
	v_cvt_pk_bf16_f32 v184, v92, v93
	v_cvt_pk_bf16_f32 v185, v94, v95
	v_cvt_pk_bf16_f32 v186, v88, v89
	v_cvt_pk_bf16_f32 v187, v90, v91
	global_store_dwordx4 v144, v[184:187], s[50:51] offset:256
	s_add_u32 s50, s50, 0x8000
	s_addc_u32 s51, s51, 0
	global_load_dwordx4 v[180:183], v[218:219], off
	global_load_dwordx4 v[184:187], v[218:219], off offset:256
	v_lshl_add_u64 v[218:219], v[218:219], 0, s[26:27]
	s_waitcnt vmcnt(6)
	v_lshlrev_b32_e32 v128, 16, v196
	v_and_b32_e32 v129, 0xffff0000, v196
	v_lshlrev_b32_e32 v130, 16, v197
	v_and_b32_e32 v131, 0xffff0000, v197
	v_lshlrev_b32_e32 v152, 16, v198
	v_and_b32_e32 v153, 0xffff0000, v198
	v_lshlrev_b32_e32 v154, 16, v199
	v_and_b32_e32 v155, 0xffff0000, v199
	v_pk_mul_f32 v[128:129], v[128:129], s[18:19]
	v_pk_mul_f32 v[130:131], v[130:131], s[18:19]
	v_pk_mul_f32 v[152:153], v[152:153], s[18:19]
	v_pk_mul_f32 v[154:155], v[154:155], s[18:19]
	v_exp_f32_e32 v128, v128
	v_exp_f32_e32 v129, v129
	v_exp_f32_e32 v130, v130
	v_exp_f32_e32 v131, v131
	v_exp_f32_e32 v152, v152
	v_exp_f32_e32 v153, v153
	v_exp_f32_e32 v154, v154
	v_exp_f32_e32 v155, v155
	v_pk_add_f32 v[128:129], v[128:129], 1.0 op_sel_hi:[1,0]
	v_pk_add_f32 v[130:131], v[130:131], 1.0 op_sel_hi:[1,0]
	v_pk_add_f32 v[152:153], v[152:153], 1.0 op_sel_hi:[1,0]
	v_pk_add_f32 v[154:155], v[154:155], 1.0 op_sel_hi:[1,0]
	v_rcp_f32_e32 v128, v128
	v_rcp_f32_e32 v129, v129
	v_rcp_f32_e32 v130, v130
	v_rcp_f32_e32 v131, v131
	v_rcp_f32_e32 v152, v152
	v_rcp_f32_e32 v153, v153
	v_rcp_f32_e32 v154, v154
	v_rcp_f32_e32 v155, v155
	v_pk_mul_f32 v[116:117], v[116:117], v[128:129]
	v_pk_mul_f32 v[118:119], v[118:119], v[130:131]
	v_pk_mul_f32 v[112:113], v[112:113], v[152:153]
	v_pk_mul_f32 v[114:115], v[114:115], v[154:155]
	v_lshlrev_b32_e32 v128, 16, v220
	v_and_b32_e32 v129, 0xffff0000, v220
	v_lshlrev_b32_e32 v130, 16, v221
	v_and_b32_e32 v131, 0xffff0000, v221
	v_lshlrev_b32_e32 v152, 16, v222
	v_and_b32_e32 v153, 0xffff0000, v222
	v_lshlrev_b32_e32 v154, 16, v223
	v_and_b32_e32 v155, 0xffff0000, v223
	v_pk_mul_f32 v[128:129], v[128:129], s[18:19]
	v_pk_mul_f32 v[130:131], v[130:131], s[18:19]
	v_pk_mul_f32 v[152:153], v[152:153], s[18:19]
; DEV unsigned cvt_pk_bf16(float lo, float hi) { const f32x2_ v = {lo, hi}; return __builtin_bit_cast(unsigned, __builtin_convertvector(v, bf16x2n_)); }
; DEV float bflo(unsigned w) { return __uint_as_float(w << 16); }
; DEV float bfhi(unsigned w) { return __uint_as_float(w & 0xffff0000u); }
;   DEV bool rescale(f32x4 (&acc)[2][2][4][2], const Unit& u, int wr, int wc, int fr, int fq) const {
;     const int row0 = u.pm * BM + wr * 64 + fr, col0 = u.pn * BM + wc * 32 + 8 * fq;
;     const bool lastseg = u.seg == 2;
;     const int sb = lastseg ? 2 : u.seg + 1;
;     const float one = lastseg ? 0.f : 1.f;
; #pragma unroll
;     for (int ai = 0; ai < 2; ++ai)
; #pragma unroll
;       for (int m = 0; m < 4; ++m) {
;         const size_t r = (size_t)(row0 + ai * HALF + m * 16);
; #pragma unroll
;         for (int bj = 0; bj < 2; ++bj) {
;           const int c = col0 + bj * HALF;
;           const u32x4 ga = *(const u32x4*)(Z + r * NIN + GT + u.seg * D + c);
;           const u32x4 gb = *(const u32x4*)(Z + r * NIN + GT + sb * D + c);
;     ...
;           acc[ai][bj][m][0][0] *= RS_(bflo(ga.x), bflo(gb.x)); acc[ai][bj][m][0][1] *= RS_(bfhi(ga.x), bfhi(gb.x));
;           acc[ai][bj][m][0][2] *= RS_(bflo(ga.y), bflo(gb.y)); acc[ai][bj][m][0][3] *= RS_(bfhi(ga.y), bfhi(gb.y));
;           acc[ai][bj][m][1][0] *= RS_(bflo(ga.z), bflo(gb.z)); acc[ai][bj][m][1][1] *= RS_(bfhi(ga.z), bfhi(gb.z));
;           acc[ai][bj][m][1][2] *= RS_(bflo(ga.w), bflo(gb.w)); acc[ai][bj][m][1][3] *= RS_(bfhi(ga.w), bfhi(gb.w));
;     ...
;           asm volatile("" ::: "memory");
;         }
;       }
;     return !lastseg;
;   }
;   DEV void operator()(const f32x4 (&acc)[2][2][4][2], const Unit& u, int wr, int wc, int fr, int fq) const {
;     const int row0 = u.pm * BM + wr * 64 + fr, col0 = u.pn * BM + wc * 32 + 8 * fq;
; #pragma unroll
;     for (int ai = 0; ai < 2; ++ai)
; #pragma unroll
;       for (int m = 0; m < 4; ++m) {
;         bf16_t* rowp = H + (size_t)(row0 + ai * HALF + m * 16) * D + col0;
; #pragma unroll
;         for (int bj = 0; bj < 2; ++bj) {
;           const f32x4 v0 = acc[ai][bj][m][0], v1 = acc[ai][bj][m][1];
;           u32x4 w; w.x = cvt_pk_bf16(v0[0], v0[1]); w.y = cvt_pk_bf16(v0[2], v0[3]); w.z = cvt_pk_bf16(v1[0], v1[1]); w.w = cvt_pk_bf16(v1[2], v1[3]);
;           *(u32x4*)(rowp + bj * HALF) = w;
;         }
;       }
;   }
	v_pk_mul_f32 v[154:155], v[154:155], s[18:19]
	v_exp_f32_e32 v128, v128
	v_exp_f32_e32 v129, v129
	v_exp_f32_e32 v130, v130
	v_exp_f32_e32 v131, v131
	v_exp_f32_e32 v152, v152
	v_exp_f32_e32 v153, v153
	v_exp_f32_e32 v154, v154
	v_exp_f32_e32 v155, v155
	v_pk_add_f32 v[128:129], v[128:129], 1.0 op_sel_hi:[1,0]
	v_pk_add_f32 v[130:131], v[130:131], 1.0 op_sel_hi:[1,0]
	v_pk_add_f32 v[152:153], v[152:153], 1.0 op_sel_hi:[1,0]
	v_pk_add_f32 v[154:155], v[154:155], 1.0 op_sel_hi:[1,0]
	v_rcp_f32_e32 v128, v128
	v_rcp_f32_e32 v129, v129
	v_rcp_f32_e32 v130, v130
	v_rcp_f32_e32 v131, v131
	v_rcp_f32_e32 v152, v152
	v_rcp_f32_e32 v153, v153
	v_rcp_f32_e32 v154, v154
	v_rcp_f32_e32 v155, v155
	v_pk_mul_f32 v[84:85], v[84:85], v[128:129]
	v_pk_mul_f32 v[86:87], v[86:87], v[130:131]
	v_pk_mul_f32 v[80:81], v[80:81], v[152:153]
	v_pk_mul_f32 v[82:83], v[82:83], v[154:155]
	v_cvt_pk_bf16_f32 v196, v116, v117
	v_cvt_pk_bf16_f32 v197, v118, v119
	v_cvt_pk_bf16_f32 v198, v112, v113
	v_cvt_pk_bf16_f32 v199, v114, v115
	global_store_dwordx4 v144, v[196:199], s[50:51]
	v_cvt_pk_bf16_f32 v220, v84, v85
	v_cvt_pk_bf16_f32 v221, v86, v87
	v_cvt_pk_bf16_f32 v222, v80, v81
	v_cvt_pk_bf16_f32 v223, v82, v83
	global_store_dwordx4 v144, v[220:223], s[50:51] offset:256
	s_add_u32 s50, s50, 0x8000
	s_addc_u32 s51, s51, 0
	global_load_dwordx4 v[196:199], v[218:219], off
	global_load_dwordx4 v[220:223], v[218:219], off offset:256
	v_lshl_add_u64 v[218:219], v[218:219], 0, s[20:21]
	s_waitcnt vmcnt(8)
	v_lshlrev_b32_e32 v128, 16, v232
	v_and_b32_e32 v129, 0xffff0000, v232
	v_lshlrev_b32_e32 v130, 16, v233
	v_and_b32_e32 v131, 0xffff0000, v233
	v_lshlrev_b32_e32 v152, 16, v234
	v_and_b32_e32 v153, 0xffff0000, v234
	v_lshlrev_b32_e32 v154, 16, v235
	v_and_b32_e32 v155, 0xffff0000, v235
	v_pk_mul_f32 v[128:129], v[128:129], s[18:19]
	v_pk_mul_f32 v[130:131], v[130:131], s[18:19]
	v_pk_mul_f32 v[152:153], v[152:153], s[18:19]
	v_pk_mul_f32 v[154:155], v[154:155], s[18:19]
	v_exp_f32_e32 v128, v128
	v_exp_f32_e32 v129, v129
	v_exp_f32_e32 v130, v130
	v_exp_f32_e32 v131, v131
	v_exp_f32_e32 v152, v152
	v_exp_f32_e32 v153, v153
	v_exp_f32_e32 v154, v154
	v_exp_f32_e32 v155, v155
	v_pk_add_f32 v[128:129], v[128:129], 1.0 op_sel_hi:[1,0]
	v_pk_add_f32 v[130:131], v[130:131], 1.0 op_sel_hi:[1,0]
	v_pk_add_f32 v[152:153], v[152:153], 1.0 op_sel_hi:[1,0]
	v_pk_add_f32 v[154:155], v[154:155], 1.0 op_sel_hi:[1,0]
	v_rcp_f32_e32 v128, v128
	v_rcp_f32_e32 v129, v129
	v_rcp_f32_e32 v130, v130
	v_rcp_f32_e32 v131, v131
	v_rcp_f32_e32 v152, v152
	v_rcp_f32_e32 v153, v153
	v_rcp_f32_e32 v154, v154
	v_rcp_f32_e32 v155, v155
	v_pk_mul_f32 v[108:109], v[108:109], v[128:129]
	v_pk_mul_f32 v[110:111], v[110:111], v[130:131]
	v_pk_mul_f32 v[104:105], v[104:105], v[152:153]
	v_pk_mul_f32 v[106:107], v[106:107], v[154:155]
	v_lshlrev_b32_e32 v128, 16, v236
	v_and_b32_e32 v129, 0xffff0000, v236
	v_lshlrev_b32_e32 v130, 16, v237
	v_and_b32_e32 v131, 0xffff0000, v237
	v_lshlrev_b32_e32 v152, 16, v238
	v_and_b32_e32 v153, 0xffff0000, v238
	v_lshlrev_b32_e32 v154, 16, v239
	v_and_b32_e32 v155, 0xffff0000, v239
	v_pk_mul_f32 v[128:129], v[128:129], s[18:19]
	v_pk_mul_f32 v[130:131], v[130:131], s[18:19]
	v_pk_mul_f32 v[152:153], v[152:153], s[18:19]
	v_pk_mul_f32 v[154:155], v[154:155], s[18:19]
	v_exp_f32_e32 v128, v128
	v_exp_f32_e32 v129, v129
	v_exp_f32_e32 v130, v130
	v_exp_f32_e32 v131, v131
	v_exp_f32_e32 v152, v152
	v_exp_f32_e32 v153, v153
	v_exp_f32_e32 v154, v154
	v_exp_f32_e32 v155, v155
	v_pk_add_f32 v[128:129], v[128:129], 1.0 op_sel_hi:[1,0]
	v_pk_add_f32 v[130:131], v[130:131], 1.0 op_sel_hi:[1,0]
	v_pk_add_f32 v[152:153], v[152:153], 1.0 op_sel_hi:[1,0]
	v_pk_add_f32 v[154:155], v[154:155], 1.0 op_sel_hi:[1,0]
	v_rcp_f32_e32 v128, v128
	v_rcp_f32_e32 v129, v129
	v_rcp_f32_e32 v130, v130
	v_rcp_f32_e32 v131, v131
	v_rcp_f32_e32 v152, v152
	v_rcp_f32_e32 v153, v153
	v_rcp_f32_e32 v154, v154
	v_rcp_f32_e32 v155, v155
	v_pk_mul_f32 v[76:77], v[76:77], v[128:129]
	v_pk_mul_f32 v[78:79], v[78:79], v[130:131]
	v_pk_mul_f32 v[72:73], v[72:73], v[152:153]
	v_pk_mul_f32 v[74:75], v[74:75], v[154:155]
	v_cvt_pk_bf16_f32 v232, v108, v109
	v_cvt_pk_bf16_f32 v233, v110, v111
	v_cvt_pk_bf16_f32 v234, v104, v105
	v_cvt_pk_bf16_f32 v235, v106, v107
	global_store_dwordx4 v144, v[232:235], s[50:51]
	v_cvt_pk_bf16_f32 v236, v76, v77
	v_cvt_pk_bf16_f32 v237, v78, v79
	v_cvt_pk_bf16_f32 v238, v72, v73
	v_cvt_pk_bf16_f32 v239, v74, v75
	global_store_dwordx4 v144, v[236:239], s[50:51] offset:256
	s_add_u32 s50, s50, 0x8000
	s_addc_u32 s51, s51, 0
	global_load_dwordx4 v[232:235], v[218:219], off
	global_load_dwordx4 v[236:239], v[218:219], off offset:256
	v_lshl_add_u64 v[218:219], v[218:219], 0, s[20:21]
	s_waitcnt vmcnt(8)
; DEV unsigned cvt_pk_bf16(float lo, float hi) { const f32x2_ v = {lo, hi}; return __builtin_bit_cast(unsigned, __builtin_convertvector(v, bf16x2n_)); }
; DEV float bflo(unsigned w) { return __uint_as_float(w << 16); }
; DEV float bfhi(unsigned w) { return __uint_as_float(w & 0xffff0000u); }
;   DEV bool rescale(f32x4 (&acc)[2][2][4][2], const Unit& u, int wr, int wc, int fr, int fq) const {
;     const int row0 = u.pm * BM + wr * 64 + fr, col0 = u.pn * BM + wc * 32 + 8 * fq;
;     const bool lastseg = u.seg == 2;
;     const int sb = lastseg ? 2 : u.seg + 1;
;     const float one = lastseg ? 0.f : 1.f;
; #pragma unroll
;     for (int ai = 0; ai < 2; ++ai)
; #pragma unroll
;       for (int m = 0; m < 4; ++m) {
;         const size_t r = (size_t)(row0 + ai * HALF + m * 16);
; #pragma unroll
;         for (int bj = 0; bj < 2; ++bj) {
;           const int c = col0 + bj * HALF;
;           const u32x4 ga = *(const u32x4*)(Z + r * NIN + GT + u.seg * D + c);
;           const u32x4 gb = *(const u32x4*)(Z + r * NIN + GT + sb * D + c);
;     ...
;           acc[ai][bj][m][0][0] *= RS_(bflo(ga.x), bflo(gb.x)); acc[ai][bj][m][0][1] *= RS_(bfhi(ga.x), bfhi(gb.x));
;           acc[ai][bj][m][0][2] *= RS_(bflo(ga.y), bflo(gb.y)); acc[ai][bj][m][0][3] *= RS_(bfhi(ga.y), bfhi(gb.y));
;           acc[ai][bj][m][1][0] *= RS_(bflo(ga.z), bflo(gb.z)); acc[ai][bj][m][1][1] *= RS_(bfhi(ga.z), bfhi(gb.z));
;           acc[ai][bj][m][1][2] *= RS_(bflo(ga.w), bflo(gb.w)); acc[ai][bj][m][1][3] *= RS_(bfhi(ga.w), bfhi(gb.w));
;     ...
;           asm volatile("" ::: "memory");
;         }
;       }
;     return !lastseg;
;   }
;   DEV void operator()(const f32x4 (&acc)[2][2][4][2], const Unit& u, int wr, int wc, int fr, int fq) const {
;     const int row0 = u.pm * BM + wr * 64 + fr, col0 = u.pn * BM + wc * 32 + 8 * fq;
; #pragma unroll
;     for (int ai = 0; ai < 2; ++ai)
; #pragma unroll
;       for (int m = 0; m < 4; ++m) {
;         bf16_t* rowp = H + (size_t)(row0 + ai * HALF + m * 16) * D + col0;
; #pragma unroll
;         for (int bj = 0; bj < 2; ++bj) {
;           const f32x4 v0 = acc[ai][bj][m][0], v1 = acc[ai][bj][m][1];
;           u32x4 w; w.x = cvt_pk_bf16(v0[0], v0[1]); w.y = cvt_pk_bf16(v0[2], v0[3]); w.z = cvt_pk_bf16(v1[0], v1[1]); w.w = cvt_pk_bf16(v1[2], v1[3]);
;           *(u32x4*)(rowp + bj * HALF) = w;
;         }
;       }
;   }
	v_lshlrev_b32_e32 v128, 16, v180
	v_and_b32_e32 v129, 0xffff0000, v180
	v_lshlrev_b32_e32 v130, 16, v181
	v_and_b32_e32 v131, 0xffff0000, v181
	v_lshlrev_b32_e32 v152, 16, v182
	v_and_b32_e32 v153, 0xffff0000, v182
	v_lshlrev_b32_e32 v154, 16, v183
	v_and_b32_e32 v155, 0xffff0000, v183
	v_pk_mul_f32 v[128:129], v[128:129], s[18:19]
	v_pk_mul_f32 v[130:131], v[130:131], s[18:19]
	v_pk_mul_f32 v[152:153], v[152:153], s[18:19]
	v_pk_mul_f32 v[154:155], v[154:155], s[18:19]
	v_exp_f32_e32 v128, v128
	v_exp_f32_e32 v129, v129
	v_exp_f32_e32 v130, v130
	v_exp_f32_e32 v131, v131
	v_exp_f32_e32 v152, v152
	v_exp_f32_e32 v153, v153
	v_exp_f32_e32 v154, v154
	v_exp_f32_e32 v155, v155
	v_pk_add_f32 v[128:129], v[128:129], 1.0 op_sel_hi:[1,0]
	v_pk_add_f32 v[130:131], v[130:131], 1.0 op_sel_hi:[1,0]
	v_pk_add_f32 v[152:153], v[152:153], 1.0 op_sel_hi:[1,0]
	v_pk_add_f32 v[154:155], v[154:155], 1.0 op_sel_hi:[1,0]
	v_rcp_f32_e32 v128, v128
	v_rcp_f32_e32 v129, v129
	v_rcp_f32_e32 v130, v130
	v_rcp_f32_e32 v131, v131
	v_rcp_f32_e32 v152, v152
	v_rcp_f32_e32 v153, v153
	v_rcp_f32_e32 v154, v154
	v_rcp_f32_e32 v155, v155
	v_pk_mul_f32 v[100:101], v[100:101], v[128:129]
	v_pk_mul_f32 v[102:103], v[102:103], v[130:131]
	v_pk_mul_f32 v[96:97], v[96:97], v[152:153]
	v_pk_mul_f32 v[98:99], v[98:99], v[154:155]
	v_lshlrev_b32_e32 v128, 16, v184
	v_and_b32_e32 v129, 0xffff0000, v184
	v_lshlrev_b32_e32 v130, 16, v185
	v_and_b32_e32 v131, 0xffff0000, v185
	v_lshlrev_b32_e32 v152, 16, v186
	v_and_b32_e32 v153, 0xffff0000, v186
	v_lshlrev_b32_e32 v154, 16, v187
	v_and_b32_e32 v155, 0xffff0000, v187
	v_pk_mul_f32 v[128:129], v[128:129], s[18:19]
	v_pk_mul_f32 v[130:131], v[130:131], s[18:19]
	v_pk_mul_f32 v[152:153], v[152:153], s[18:19]
	v_pk_mul_f32 v[154:155], v[154:155], s[18:19]
	v_exp_f32_e32 v128, v128
	v_exp_f32_e32 v129, v129
	v_exp_f32_e32 v130, v130
	v_exp_f32_e32 v131, v131
	v_exp_f32_e32 v152, v152
	v_exp_f32_e32 v153, v153
	v_exp_f32_e32 v154, v154
	v_exp_f32_e32 v155, v155
	v_pk_add_f32 v[128:129], v[128:129], 1.0 op_sel_hi:[1,0]
	v_pk_add_f32 v[130:131], v[130:131], 1.0 op_sel_hi:[1,0]
	v_pk_add_f32 v[152:153], v[152:153], 1.0 op_sel_hi:[1,0]
	v_pk_add_f32 v[154:155], v[154:155], 1.0 op_sel_hi:[1,0]
	v_rcp_f32_e32 v128, v128
	v_rcp_f32_e32 v129, v129
	v_rcp_f32_e32 v130, v130
	v_rcp_f32_e32 v131, v131
	v_rcp_f32_e32 v152, v152
	v_rcp_f32_e32 v153, v153
	v_rcp_f32_e32 v154, v154
	v_rcp_f32_e32 v155, v155
	v_pk_mul_f32 v[68:69], v[68:69], v[128:129]
	v_pk_mul_f32 v[70:71], v[70:71], v[130:131]
	v_pk_mul_f32 v[64:65], v[64:65], v[152:153]
	v_pk_mul_f32 v[66:67], v[66:67], v[154:155]
	v_cvt_pk_bf16_f32 v180, v100, v101
	v_cvt_pk_bf16_f32 v181, v102, v103
	v_cvt_pk_bf16_f32 v182, v96, v97
	v_cvt_pk_bf16_f32 v183, v98, v99
	global_store_dwordx4 v144, v[180:183], s[50:51]
	v_cvt_pk_bf16_f32 v184, v68, v69
	v_cvt_pk_bf16_f32 v185, v70, v71
	v_cvt_pk_bf16_f32 v186, v64, v65
	v_cvt_pk_bf16_f32 v187, v66, v67
	global_store_dwordx4 v144, v[184:187], s[50:51] offset:256
	s_add_u32 s50, s50, 0x28000
	s_addc_u32 s51, s51, 0
	global_load_dwordx4 v[180:183], v[218:219], off
	global_load_dwordx4 v[184:187], v[218:219], off offset:256
	v_lshl_add_u64 v[218:219], v[218:219], 0, s[20:21]
	s_waitcnt vmcnt(8)
	v_lshlrev_b32_e32 v128, 16, v196
	v_and_b32_e32 v129, 0xffff0000, v196
	v_lshlrev_b32_e32 v130, 16, v197
	v_and_b32_e32 v131, 0xffff0000, v197
	v_lshlrev_b32_e32 v152, 16, v198
	v_and_b32_e32 v153, 0xffff0000, v198
	v_lshlrev_b32_e32 v154, 16, v199
	v_and_b32_e32 v155, 0xffff0000, v199
	v_pk_mul_f32 v[128:129], v[128:129], s[18:19]
	v_pk_mul_f32 v[130:131], v[130:131], s[18:19]
	v_pk_mul_f32 v[152:153], v[152:153], s[18:19]
	v_pk_mul_f32 v[154:155], v[154:155], s[18:19]
	v_exp_f32_e32 v128, v128
	v_exp_f32_e32 v129, v129
	v_exp_f32_e32 v130, v130
	v_exp_f32_e32 v131, v131
	v_exp_f32_e32 v152, v152
	v_exp_f32_e32 v153, v153
	v_exp_f32_e32 v154, v154
	v_exp_f32_e32 v155, v155
	v_pk_add_f32 v[128:129], v[128:129], 1.0 op_sel_hi:[1,0]
	v_pk_add_f32 v[130:131], v[130:131], 1.0 op_sel_hi:[1,0]
	v_pk_add_f32 v[152:153], v[152:153], 1.0 op_sel_hi:[1,0]
	v_pk_add_f32 v[154:155], v[154:155], 1.0 op_sel_hi:[1,0]
	v_rcp_f32_e32 v128, v128
	v_rcp_f32_e32 v129, v129
	v_rcp_f32_e32 v130, v130
	v_rcp_f32_e32 v131, v131
	v_rcp_f32_e32 v152, v152
	v_rcp_f32_e32 v153, v153
	v_rcp_f32_e32 v154, v154
	v_rcp_f32_e32 v155, v155
	v_pk_mul_f32 v[60:61], v[60:61], v[128:129]
	v_pk_mul_f32 v[62:63], v[62:63], v[130:131]
	v_pk_mul_f32 v[56:57], v[56:57], v[152:153]
	v_pk_mul_f32 v[58:59], v[58:59], v[154:155]
	v_lshlrev_b32_e32 v128, 16, v220
	v_and_b32_e32 v129, 0xffff0000, v220
	v_lshlrev_b32_e32 v130, 16, v221
	v_and_b32_e32 v131, 0xffff0000, v221
	v_lshlrev_b32_e32 v152, 16, v222
	v_and_b32_e32 v153, 0xffff0000, v222
	v_lshlrev_b32_e32 v154, 16, v223
	v_and_b32_e32 v155, 0xffff0000, v223
	v_pk_mul_f32 v[128:129], v[128:129], s[18:19]
	v_pk_mul_f32 v[130:131], v[130:131], s[18:19]
	v_pk_mul_f32 v[152:153], v[152:153], s[18:19]
	v_pk_mul_f32 v[154:155], v[154:155], s[18:19]
	v_exp_f32_e32 v128, v128
	v_exp_f32_e32 v129, v129
	v_exp_f32_e32 v130, v130
	v_exp_f32_e32 v131, v131
	v_exp_f32_e32 v152, v152
	v_exp_f32_e32 v153, v153
	v_exp_f32_e32 v154, v154
	v_exp_f32_e32 v155, v155
	v_pk_add_f32 v[128:129], v[128:129], 1.0 op_sel_hi:[1,0]
	v_pk_add_f32 v[130:131], v[130:131], 1.0 op_sel_hi:[1,0]
	v_pk_add_f32 v[152:153], v[152:153], 1.0 op_sel_hi:[1,0]
	v_pk_add_f32 v[154:155], v[154:155], 1.0 op_sel_hi:[1,0]
	v_rcp_f32_e32 v128, v128
	v_rcp_f32_e32 v129, v129
	v_rcp_f32_e32 v130, v130
	v_rcp_f32_e32 v131, v131
	v_rcp_f32_e32 v152, v152
	v_rcp_f32_e32 v153, v153
	v_rcp_f32_e32 v154, v154
	v_rcp_f32_e32 v155, v155
	v_pk_mul_f32 v[28:29], v[28:29], v[128:129]
	v_pk_mul_f32 v[30:31], v[30:31], v[130:131]
	v_pk_mul_f32 v[24:25], v[24:25], v[152:153]
	v_pk_mul_f32 v[26:27], v[26:27], v[154:155]
	v_cvt_pk_bf16_f32 v196, v60, v61
	v_cvt_pk_bf16_f32 v197, v62, v63
	v_cvt_pk_bf16_f32 v198, v56, v57
	v_cvt_pk_bf16_f32 v199, v58, v59
	global_store_dwordx4 v144, v[196:199], s[50:51]
	v_cvt_pk_bf16_f32 v220, v28, v29
	v_cvt_pk_bf16_f32 v221, v30, v31
	v_cvt_pk_bf16_f32 v222, v24, v25
	v_cvt_pk_bf16_f32 v223, v26, v27
	global_store_dwordx4 v144, v[220:223], s[50:51] offset:256
	s_add_u32 s50, s50, 0x8000
	s_addc_u32 s51, s51, 0
	global_load_dwordx4 v[196:199], v[218:219], off
	global_load_dwordx4 v[220:223], v[218:219], off offset:256
	s_waitcnt vmcnt(8)
; DEV unsigned cvt_pk_bf16(float lo, float hi) { const f32x2_ v = {lo, hi}; return __builtin_bit_cast(unsigned, __builtin_convertvector(v, bf16x2n_)); }
; DEV float bflo(unsigned w) { return __uint_as_float(w << 16); }
; DEV float bfhi(unsigned w) { return __uint_as_float(w & 0xffff0000u); }
;   DEV bool rescale(f32x4 (&acc)[2][2][4][2], const Unit& u, int wr, int wc, int fr, int fq) const {
;     const int row0 = u.pm * BM + wr * 64 + fr, col0 = u.pn * BM + wc * 32 + 8 * fq;
;     const bool lastseg = u.seg == 2;
;     const int sb = lastseg ? 2 : u.seg + 1;
;     const float one = lastseg ? 0.f : 1.f;
; #pragma unroll
;     for (int ai = 0; ai < 2; ++ai)
; #pragma unroll
;       for (int m = 0; m < 4; ++m) {
;         const size_t r = (size_t)(row0 + ai * HALF + m * 16);
; #pragma unroll
;         for (int bj = 0; bj < 2; ++bj) {
;           const int c = col0 + bj * HALF;
;           const u32x4 ga = *(const u32x4*)(Z + r * NIN + GT + u.seg * D + c);
;           const u32x4 gb = *(const u32x4*)(Z + r * NIN + GT + sb * D + c);
;     ...
;           acc[ai][bj][m][0][0] *= RS_(bflo(ga.x), bflo(gb.x)); acc[ai][bj][m][0][1] *= RS_(bfhi(ga.x), bfhi(gb.x));
;           acc[ai][bj][m][0][2] *= RS_(bflo(ga.y), bflo(gb.y)); acc[ai][bj][m][0][3] *= RS_(bfhi(ga.y), bfhi(gb.y));
;           acc[ai][bj][m][1][0] *= RS_(bflo(ga.z), bflo(gb.z)); acc[ai][bj][m][1][1] *= RS_(bfhi(ga.z), bfhi(gb.z));
;           acc[ai][bj][m][1][2] *= RS_(bflo(ga.w), bflo(gb.w)); acc[ai][bj][m][1][3] *= RS_(bfhi(ga.w), bfhi(gb.w));
;     ...
;           asm volatile("" ::: "memory");
;         }
;       }
;     return !lastseg;
;   }
;   DEV void operator()(const f32x4 (&acc)[2][2][4][2], const Unit& u, int wr, int wc, int fr, int fq) const {
;     const int row0 = u.pm * BM + wr * 64 + fr, col0 = u.pn * BM + wc * 32 + 8 * fq;
; #pragma unroll
;     for (int ai = 0; ai < 2; ++ai)
; #pragma unroll
;       for (int m = 0; m < 4; ++m) {
;         bf16_t* rowp = H + (size_t)(row0 + ai * HALF + m * 16) * D + col0;
; #pragma unroll
;         for (int bj = 0; bj < 2; ++bj) {
;           const f32x4 v0 = acc[ai][bj][m][0], v1 = acc[ai][bj][m][1];
;           u32x4 w; w.x = cvt_pk_bf16(v0[0], v0[1]); w.y = cvt_pk_bf16(v0[2], v0[3]); w.z = cvt_pk_bf16(v1[0], v1[1]); w.w = cvt_pk_bf16(v1[2], v1[3]);
;           *(u32x4*)(rowp + bj * HALF) = w;
;         }
;       }
;   }
	v_lshlrev_b32_e32 v128, 16, v232
	v_and_b32_e32 v129, 0xffff0000, v232
	v_lshlrev_b32_e32 v130, 16, v233
	v_and_b32_e32 v131, 0xffff0000, v233
	v_lshlrev_b32_e32 v152, 16, v234
	v_and_b32_e32 v153, 0xffff0000, v234
	v_lshlrev_b32_e32 v154, 16, v235
	v_and_b32_e32 v155, 0xffff0000, v235
	v_pk_mul_f32 v[128:129], v[128:129], s[18:19]
	v_pk_mul_f32 v[130:131], v[130:131], s[18:19]
	v_pk_mul_f32 v[152:153], v[152:153], s[18:19]
	v_pk_mul_f32 v[154:155], v[154:155], s[18:19]
	v_exp_f32_e32 v128, v128
	v_exp_f32_e32 v129, v129
	v_exp_f32_e32 v130, v130
	v_exp_f32_e32 v131, v131
	v_exp_f32_e32 v152, v152
	v_exp_f32_e32 v153, v153
	v_exp_f32_e32 v154, v154
	v_exp_f32_e32 v155, v155
	v_pk_add_f32 v[128:129], v[128:129], 1.0 op_sel_hi:[1,0]
	v_pk_add_f32 v[130:131], v[130:131], 1.0 op_sel_hi:[1,0]
	v_pk_add_f32 v[152:153], v[152:153], 1.0 op_sel_hi:[1,0]
	v_pk_add_f32 v[154:155], v[154:155], 1.0 op_sel_hi:[1,0]
	v_rcp_f32_e32 v128, v128
	v_rcp_f32_e32 v129, v129
	v_rcp_f32_e32 v130, v130
	v_rcp_f32_e32 v131, v131
	v_rcp_f32_e32 v152, v152
	v_rcp_f32_e32 v153, v153
	v_rcp_f32_e32 v154, v154
	v_rcp_f32_e32 v155, v155
	v_pk_mul_f32 v[52:53], v[52:53], v[128:129]
	v_pk_mul_f32 v[54:55], v[54:55], v[130:131]
	v_pk_mul_f32 v[48:49], v[48:49], v[152:153]
	v_pk_mul_f32 v[50:51], v[50:51], v[154:155]
	v_lshlrev_b32_e32 v128, 16, v236
	v_and_b32_e32 v129, 0xffff0000, v236
	v_lshlrev_b32_e32 v130, 16, v237
	v_and_b32_e32 v131, 0xffff0000, v237
	v_lshlrev_b32_e32 v152, 16, v238
	v_and_b32_e32 v153, 0xffff0000, v238
	v_lshlrev_b32_e32 v154, 16, v239
	v_and_b32_e32 v155, 0xffff0000, v239
	v_pk_mul_f32 v[128:129], v[128:129], s[18:19]
	v_pk_mul_f32 v[130:131], v[130:131], s[18:19]
	v_pk_mul_f32 v[152:153], v[152:153], s[18:19]
	v_pk_mul_f32 v[154:155], v[154:155], s[18:19]
	v_exp_f32_e32 v128, v128
	v_exp_f32_e32 v129, v129
	v_exp_f32_e32 v130, v130
	v_exp_f32_e32 v131, v131
	v_exp_f32_e32 v152, v152
	v_exp_f32_e32 v153, v153
	v_exp_f32_e32 v154, v154
	v_exp_f32_e32 v155, v155
	v_pk_add_f32 v[128:129], v[128:129], 1.0 op_sel_hi:[1,0]
	v_pk_add_f32 v[130:131], v[130:131], 1.0 op_sel_hi:[1,0]
	v_pk_add_f32 v[152:153], v[152:153], 1.0 op_sel_hi:[1,0]
	v_pk_add_f32 v[154:155], v[154:155], 1.0 op_sel_hi:[1,0]
	v_rcp_f32_e32 v128, v128
	v_rcp_f32_e32 v129, v129
	v_rcp_f32_e32 v130, v130
	v_rcp_f32_e32 v131, v131
	v_rcp_f32_e32 v152, v152
	v_rcp_f32_e32 v153, v153
	v_rcp_f32_e32 v154, v154
	v_rcp_f32_e32 v155, v155
	v_pk_mul_f32 v[20:21], v[20:21], v[128:129]
	v_pk_mul_f32 v[22:23], v[22:23], v[130:131]
	v_pk_mul_f32 v[16:17], v[16:17], v[152:153]
	v_pk_mul_f32 v[18:19], v[18:19], v[154:155]
	v_cvt_pk_bf16_f32 v232, v52, v53
	v_cvt_pk_bf16_f32 v233, v54, v55
	v_cvt_pk_bf16_f32 v234, v48, v49
	v_cvt_pk_bf16_f32 v235, v50, v51
	global_store_dwordx4 v144, v[232:235], s[50:51]
	v_cvt_pk_bf16_f32 v236, v20, v21
	v_cvt_pk_bf16_f32 v237, v22, v23
	v_cvt_pk_bf16_f32 v238, v16, v17
	v_cvt_pk_bf16_f32 v239, v18, v19
	global_store_dwordx4 v144, v[236:239], s[50:51] offset:256
	s_add_u32 s50, s50, 0x8000
	s_addc_u32 s51, s51, 0
	s_waitcnt vmcnt(6)
; DEV unsigned cvt_pk_bf16(float lo, float hi) { const f32x2_ v = {lo, hi}; return __builtin_bit_cast(unsigned, __builtin_convertvector(v, bf16x2n_)); }
; DEV float bflo(unsigned w) { return __uint_as_float(w << 16); }
; DEV float bfhi(unsigned w) { return __uint_as_float(w & 0xffff0000u); }
;   DEV bool rescale(f32x4 (&acc)[2][2][4][2], const Unit& u, int wr, int wc, int fr, int fq) const {
;     const int row0 = u.pm * BM + wr * 64 + fr, col0 = u.pn * BM + wc * 32 + 8 * fq;
;     const bool lastseg = u.seg == 2;
;     const int sb = lastseg ? 2 : u.seg + 1;
;     const float one = lastseg ? 0.f : 1.f;
; #pragma unroll
;     for (int ai = 0; ai < 2; ++ai)
; #pragma unroll
;       for (int m = 0; m < 4; ++m) {
;         const size_t r = (size_t)(row0 + ai * HALF + m * 16);
; #pragma unroll
;         for (int bj = 0; bj < 2; ++bj) {
;           const int c = col0 + bj * HALF;
;           const u32x4 ga = *(const u32x4*)(Z + r * NIN + GT + u.seg * D + c);
;           const u32x4 gb = *(const u32x4*)(Z + r * NIN + GT + sb * D + c);
;     ...
;           acc[ai][bj][m][0][0] *= RS_(bflo(ga.x), bflo(gb.x)); acc[ai][bj][m][0][1] *= RS_(bfhi(ga.x), bfhi(gb.x));
;           acc[ai][bj][m][0][2] *= RS_(bflo(ga.y), bflo(gb.y)); acc[ai][bj][m][0][3] *= RS_(bfhi(ga.y), bfhi(gb.y));
;           acc[ai][bj][m][1][0] *= RS_(bflo(ga.z), bflo(gb.z)); acc[ai][bj][m][1][1] *= RS_(bfhi(ga.z), bfhi(gb.z));
;           acc[ai][bj][m][1][2] *= RS_(bflo(ga.w), bflo(gb.w)); acc[ai][bj][m][1][3] *= RS_(bfhi(ga.w), bfhi(gb.w));
;     ...
;           asm volatile("" ::: "memory");
;         }
;       }
;     return !lastseg;
;   }
;   DEV void operator()(const f32x4 (&acc)[2][2][4][2], const Unit& u, int wr, int wc, int fr, int fq) const {
;     const int row0 = u.pm * BM + wr * 64 + fr, col0 = u.pn * BM + wc * 32 + 8 * fq;
; #pragma unroll
;     for (int ai = 0; ai < 2; ++ai)
; #pragma unroll
;       for (int m = 0; m < 4; ++m) {
;         bf16_t* rowp = H + (size_t)(row0 + ai * HALF + m * 16) * D + col0;
; #pragma unroll
;         for (int bj = 0; bj < 2; ++bj) {
;           const f32x4 v0 = acc[ai][bj][m][0], v1 = acc[ai][bj][m][1];
;           u32x4 w; w.x = cvt_pk_bf16(v0[0], v0[1]); w.y = cvt_pk_bf16(v0[2], v0[3]); w.z = cvt_pk_bf16(v1[0], v1[1]); w.w = cvt_pk_bf16(v1[2], v1[3]);
;           *(u32x4*)(rowp + bj * HALF) = w;
;         }
;       }
;   }
	v_lshlrev_b32_e32 v128, 16, v180
	v_and_b32_e32 v129, 0xffff0000, v180
	v_lshlrev_b32_e32 v130, 16, v181
	v_and_b32_e32 v131, 0xffff0000, v181
	v_lshlrev_b32_e32 v152, 16, v182
	v_and_b32_e32 v153, 0xffff0000, v182
	v_lshlrev_b32_e32 v154, 16, v183
	v_and_b32_e32 v155, 0xffff0000, v183
	v_pk_mul_f32 v[128:129], v[128:129], s[18:19]
	v_pk_mul_f32 v[130:131], v[130:131], s[18:19]
	v_pk_mul_f32 v[152:153], v[152:153], s[18:19]
	v_pk_mul_f32 v[154:155], v[154:155], s[18:19]
	v_exp_f32_e32 v128, v128
	v_exp_f32_e32 v129, v129
	v_exp_f32_e32 v130, v130
	v_exp_f32_e32 v131, v131
	v_exp_f32_e32 v152, v152
	v_exp_f32_e32 v153, v153
	v_exp_f32_e32 v154, v154
	v_exp_f32_e32 v155, v155
	v_pk_add_f32 v[128:129], v[128:129], 1.0 op_sel_hi:[1,0]
	v_pk_add_f32 v[130:131], v[130:131], 1.0 op_sel_hi:[1,0]
	v_pk_add_f32 v[152:153], v[152:153], 1.0 op_sel_hi:[1,0]
	v_pk_add_f32 v[154:155], v[154:155], 1.0 op_sel_hi:[1,0]
	v_rcp_f32_e32 v128, v128
	v_rcp_f32_e32 v129, v129
	v_rcp_f32_e32 v130, v130
	v_rcp_f32_e32 v131, v131
	v_rcp_f32_e32 v152, v152
	v_rcp_f32_e32 v153, v153
	v_rcp_f32_e32 v154, v154
	v_rcp_f32_e32 v155, v155
	v_pk_mul_f32 v[44:45], v[44:45], v[128:129]
	v_pk_mul_f32 v[46:47], v[46:47], v[130:131]
	v_pk_mul_f32 v[40:41], v[40:41], v[152:153]
	v_pk_mul_f32 v[42:43], v[42:43], v[154:155]
	v_lshlrev_b32_e32 v128, 16, v184
	v_and_b32_e32 v129, 0xffff0000, v184
	v_lshlrev_b32_e32 v130, 16, v185
	v_and_b32_e32 v131, 0xffff0000, v185
	v_lshlrev_b32_e32 v152, 16, v186
	v_and_b32_e32 v153, 0xffff0000, v186
	v_lshlrev_b32_e32 v154, 16, v187
	v_and_b32_e32 v155, 0xffff0000, v187
	v_pk_mul_f32 v[128:129], v[128:129], s[18:19]
	v_pk_mul_f32 v[130:131], v[130:131], s[18:19]
	v_pk_mul_f32 v[152:153], v[152:153], s[18:19]
	v_pk_mul_f32 v[154:155], v[154:155], s[18:19]
	v_exp_f32_e32 v128, v128
	v_exp_f32_e32 v129, v129
	v_exp_f32_e32 v130, v130
	v_exp_f32_e32 v131, v131
	v_exp_f32_e32 v152, v152
	v_exp_f32_e32 v153, v153
	v_exp_f32_e32 v154, v154
	v_exp_f32_e32 v155, v155
	v_pk_add_f32 v[128:129], v[128:129], 1.0 op_sel_hi:[1,0]
	v_pk_add_f32 v[130:131], v[130:131], 1.0 op_sel_hi:[1,0]
	v_pk_add_f32 v[152:153], v[152:153], 1.0 op_sel_hi:[1,0]
	v_pk_add_f32 v[154:155], v[154:155], 1.0 op_sel_hi:[1,0]
	v_rcp_f32_e32 v128, v128
	v_rcp_f32_e32 v129, v129
	v_rcp_f32_e32 v130, v130
	v_rcp_f32_e32 v131, v131
	v_rcp_f32_e32 v152, v152
	v_rcp_f32_e32 v153, v153
	v_rcp_f32_e32 v154, v154
	v_rcp_f32_e32 v155, v155
	v_pk_mul_f32 v[12:13], v[12:13], v[128:129]
	v_pk_mul_f32 v[14:15], v[14:15], v[130:131]
	v_pk_mul_f32 v[8:9], v[8:9], v[152:153]
	v_pk_mul_f32 v[10:11], v[10:11], v[154:155]
	v_cvt_pk_bf16_f32 v180, v44, v45
	v_cvt_pk_bf16_f32 v181, v46, v47
	v_cvt_pk_bf16_f32 v182, v40, v41
	v_cvt_pk_bf16_f32 v183, v42, v43
	global_store_dwordx4 v144, v[180:183], s[50:51]
	v_cvt_pk_bf16_f32 v184, v12, v13
	v_cvt_pk_bf16_f32 v185, v14, v15
	v_cvt_pk_bf16_f32 v186, v8, v9
	v_cvt_pk_bf16_f32 v187, v10, v11
	global_store_dwordx4 v144, v[184:187], s[50:51] offset:256
	s_add_u32 s50, s50, 0x8000
	s_addc_u32 s51, s51, 0
	s_waitcnt vmcnt(4)
	v_lshlrev_b32_e32 v128, 16, v196
	v_and_b32_e32 v129, 0xffff0000, v196
	v_lshlrev_b32_e32 v130, 16, v197
	v_and_b32_e32 v131, 0xffff0000, v197
	v_lshlrev_b32_e32 v152, 16, v198
	v_and_b32_e32 v153, 0xffff0000, v198
	v_lshlrev_b32_e32 v154, 16, v199
	v_and_b32_e32 v155, 0xffff0000, v199
	v_pk_mul_f32 v[128:129], v[128:129], s[18:19]
	v_pk_mul_f32 v[130:131], v[130:131], s[18:19]
	v_pk_mul_f32 v[152:153], v[152:153], s[18:19]
	v_pk_mul_f32 v[154:155], v[154:155], s[18:19]
	v_exp_f32_e32 v128, v128
	v_exp_f32_e32 v129, v129
	v_exp_f32_e32 v130, v130
	v_exp_f32_e32 v131, v131
	v_exp_f32_e32 v152, v152
	v_exp_f32_e32 v153, v153
	v_exp_f32_e32 v154, v154
	v_exp_f32_e32 v155, v155
	v_pk_add_f32 v[128:129], v[128:129], 1.0 op_sel_hi:[1,0]
	v_pk_add_f32 v[130:131], v[130:131], 1.0 op_sel_hi:[1,0]
	v_pk_add_f32 v[152:153], v[152:153], 1.0 op_sel_hi:[1,0]
	v_pk_add_f32 v[154:155], v[154:155], 1.0 op_sel_hi:[1,0]
	v_rcp_f32_e32 v128, v128
	v_rcp_f32_e32 v129, v129
	v_rcp_f32_e32 v130, v130
	v_rcp_f32_e32 v131, v131
	v_rcp_f32_e32 v152, v152
	v_rcp_f32_e32 v153, v153
	v_rcp_f32_e32 v154, v154
	v_rcp_f32_e32 v155, v155
	v_pk_mul_f32 v[36:37], v[36:37], v[128:129]
	v_pk_mul_f32 v[38:39], v[38:39], v[130:131]
	v_pk_mul_f32 v[32:33], v[32:33], v[152:153]
	v_pk_mul_f32 v[34:35], v[34:35], v[154:155]
	v_lshlrev_b32_e32 v128, 16, v220
	v_and_b32_e32 v129, 0xffff0000, v220
	v_lshlrev_b32_e32 v130, 16, v221
	v_and_b32_e32 v131, 0xffff0000, v221
	v_lshlrev_b32_e32 v152, 16, v222
	v_and_b32_e32 v153, 0xffff0000, v222
	v_lshlrev_b32_e32 v154, 16, v223
	v_and_b32_e32 v155, 0xffff0000, v223
	v_pk_mul_f32 v[128:129], v[128:129], s[18:19]
	v_pk_mul_f32 v[130:131], v[130:131], s[18:19]
	v_pk_mul_f32 v[152:153], v[152:153], s[18:19]
	v_pk_mul_f32 v[154:155], v[154:155], s[18:19]
	v_exp_f32_e32 v128, v128
	v_exp_f32_e32 v129, v129
	v_exp_f32_e32 v130, v130
	v_exp_f32_e32 v131, v131
	v_exp_f32_e32 v152, v152
	v_exp_f32_e32 v153, v153
	v_exp_f32_e32 v154, v154
	v_exp_f32_e32 v155, v155
	v_pk_add_f32 v[128:129], v[128:129], 1.0 op_sel_hi:[1,0]
	v_pk_add_f32 v[130:131], v[130:131], 1.0 op_sel_hi:[1,0]
	v_pk_add_f32 v[152:153], v[152:153], 1.0 op_sel_hi:[1,0]
	v_pk_add_f32 v[154:155], v[154:155], 1.0 op_sel_hi:[1,0]
	v_rcp_f32_e32 v128, v128
	v_rcp_f32_e32 v129, v129
	v_rcp_f32_e32 v130, v130
	v_rcp_f32_e32 v131, v131
	v_rcp_f32_e32 v152, v152
	v_rcp_f32_e32 v153, v153
	v_rcp_f32_e32 v154, v154
	v_rcp_f32_e32 v155, v155
	v_pk_mul_f32 v[4:5], v[4:5], v[128:129]
	v_pk_mul_f32 v[6:7], v[6:7], v[130:131]
	v_pk_mul_f32 v[0:1], v[0:1], v[152:153]
	v_pk_mul_f32 v[2:3], v[2:3], v[154:155]
	v_cvt_pk_bf16_f32 v196, v36, v37
	v_cvt_pk_bf16_f32 v197, v38, v39
	v_cvt_pk_bf16_f32 v198, v32, v33
	v_cvt_pk_bf16_f32 v199, v34, v35
	global_store_dwordx4 v144, v[196:199], s[50:51]
	v_cvt_pk_bf16_f32 v220, v4, v5
	v_cvt_pk_bf16_f32 v221, v6, v7
	v_cvt_pk_bf16_f32 v222, v0, v1
	v_cvt_pk_bf16_f32 v223, v2, v3
	global_store_dwordx4 v144, v[220:223], s[50:51] offset:256
